# v33 + MLA attention loops: per-cluster s_setprio flips removed, one static s_setprio 1 for waves 4-7 during the loop
# speedup vs baseline: 1.0004x; 1.0004x over previous
; DI float bf_lo(unsigned u) { return __uint_as_float(u << 16); }
; DI float bf_hi(unsigned u) { return __uint_as_float(u & 0xffff0000u); }
; template <int DQK, int KROW, bool BIAS, bool MAPS2>
; DI void attn_core(const int t, const u16* __restrict__ Q, int ldq, const u16* __restrict__ Kp, int ldk, const u16* __restrict__ Vt, int q0,
;                   char* lds, const float* lut, float b31, f32x16 (&o)[4], float& l_out) {
;     ...
;   l_out = xhalf_sum(l_run);
; }
; DI void mla_unit(const Params& p, const int t, int l, int h, int qb, char* lds) {
;     ...
;   const float inv = 1.0f / lsum;
;   u32x2 zv[16];
; #pragma unroll
;   for (int dt = 0; dt < 4; ++dt)
; #pragma unroll
;     for (int g = 0; g < 4; ++g) zv[dt * 4 + g] = *(const u32x2*)(p.ZG + (size_t)qrow * 2048 + 1024 + h * 128 + 32 * dt + 8 * g + 4 * hf);
; #pragma unroll
;   for (int dt = 0; dt < 4; ++dt)
; #pragma unroll
;     for (int a = 0; a < 2; ++a) {
;       float xy[2][4];
; #pragma unroll
;       for (int q2 = 0; q2 < 2; ++q2) {
;         const int g = 2 * a + q2;
;         const u32x2 z = zv[dt * 4 + g];
;         xy[q2][0] = o[dt][4 * g] * inv * bf_lo(z[0]); xy[q2][1] = o[dt][4 * g + 1] * inv * bf_hi(z[0]);
;         xy[q2][2] = o[dt][4 * g + 2] * inv * bf_lo(z[1]); xy[q2][3] = o[dt][4 * g + 3] * inv * bf_hi(z[1]);
;       }
;       st8_pair_bf16(p.MIX + (size_t)qrow * 2048 + 1024 + h * 128 + 32 * dt + 16 * a + 8 * hf, xy[0], xy[1]);
;     }
.LBB0_214:
	s_setprio 0
	v_mov_b32_e32 v66, v0
	s_nop 1
	v_permlane32_swap_b32_e32 v0, v66
	v_lshlrev_b64 v[96:97], 12, v[170:171]
	v_add_f32_e32 v68, v0, v66
	v_lshl_add_u64 v[66:67], s[48:49], 0, v[96:97]
	s_lshl_b64 s[0:1], s[88:89], 1
	v_lshl_add_u64 v[66:67], v[66:67], 0, s[0:1]
	v_lshlrev_b32_e32 v0, 1, v176
	v_lshl_add_u64 v[66:67], v[66:67], 0, v[0:1]
	global_load_dwordx2 v[98:99], v[66:67], off offset:2048
	global_load_dwordx2 v[100:101], v[66:67], off offset:2064
	global_load_dwordx2 v[94:95], v[66:67], off offset:2080
	global_load_dwordx2 v[92:93], v[66:67], off offset:2096
	global_load_dwordx2 v[90:91], v[66:67], off offset:2112
	global_load_dwordx2 v[88:89], v[66:67], off offset:2128
	global_load_dwordx2 v[86:87], v[66:67], off offset:2144
	global_load_dwordx2 v[84:85], v[66:67], off offset:2160
	global_load_dwordx2 v[82:83], v[66:67], off offset:2176
	global_load_dwordx2 v[80:81], v[66:67], off offset:2192
	global_load_dwordx2 v[78:79], v[66:67], off offset:2208
	global_load_dwordx2 v[76:77], v[66:67], off offset:2224
	global_load_dwordx2 v[74:75], v[66:67], off offset:2240
	global_load_dwordx2 v[72:73], v[66:67], off offset:2256
	global_load_dwordx2 v[70:71], v[66:67], off offset:2272
	s_nop 0
	global_load_dwordx2 v[66:67], v[66:67], off offset:2288
	v_div_scale_f32 v0, s[62:63], v68, v68, 1.0
	v_rcp_f32_e32 v69, v0
	s_waitcnt vmcnt(31)
	v_fma_f32 v102, -v0, v69, 1.0
	v_fmac_f32_e32 v69, v102, v69
	v_div_scale_f32 v102, vcc, 1.0, v68, 1.0
	v_mul_f32_e32 v103, v102, v69
	v_fma_f32 v104, -v0, v103, v102
	v_fmac_f32_e32 v103, v104, v69
	v_fma_f32 v0, -v0, v103, v102
	v_div_fmas_f32 v0, v0, v69, v103
	v_div_fixup_f32 v68, v0, v68, 1.0
	v_pk_mul_f32 v[50:51], v[50:51], v[68:69] op_sel_hi:[1,0]
	v_lshlrev_b32_e32 v0, 1, v166
	v_pk_mul_f32 v[34:35], v[34:35], v[68:69] op_sel_hi:[1,0]
	v_pk_mul_f32 v[36:37], v[36:37], v[68:69] op_sel_hi:[1,0]
	v_pk_mul_f32 v[38:39], v[38:39], v[68:69] op_sel_hi:[1,0]
	v_pk_mul_f32 v[40:41], v[40:41], v[68:69] op_sel_hi:[1,0]
	v_pk_mul_f32 v[18:19], v[18:19], v[68:69] op_sel_hi:[1,0]
	v_pk_mul_f32 v[20:21], v[20:21], v[68:69] op_sel_hi:[1,0]
	v_pk_mul_f32 v[22:23], v[22:23], v[68:69] op_sel_hi:[1,0]
	v_pk_mul_f32 v[24:25], v[24:25], v[68:69] op_sel_hi:[1,0]
	v_pk_mul_f32 v[2:3], v[2:3], v[68:69] op_sel_hi:[1,0]
	v_pk_mul_f32 v[4:5], v[4:5], v[68:69] op_sel_hi:[1,0]
	v_pk_mul_f32 v[6:7], v[6:7], v[68:69] op_sel_hi:[1,0]
	v_pk_mul_f32 v[8:9], v[8:9], v[68:69] op_sel_hi:[1,0]
	s_waitcnt vmcnt(15)
	v_lshlrev_b32_e32 v102, 16, v98
	v_and_b32_e32 v103, 0xffff0000, v98
	v_pk_mul_f32 v[102:103], v[50:51], v[102:103]
	v_pk_mul_f32 v[50:51], v[52:53], v[68:69] op_sel_hi:[1,0]
	v_lshlrev_b32_e32 v52, 16, v99
	v_and_b32_e32 v53, 0xffff0000, v99
	v_pk_mul_f32 v[98:99], v[50:51], v[52:53]
	v_pk_mul_f32 v[50:51], v[54:55], v[68:69] op_sel_hi:[1,0]
	s_waitcnt vmcnt(14)
	v_lshlrev_b32_e32 v52, 16, v100
	v_and_b32_e32 v53, 0xffff0000, v100
	v_pk_mul_f32 v[54:55], v[50:51], v[52:53]
	v_pk_mul_f32 v[50:51], v[56:57], v[68:69] op_sel_hi:[1,0]
	v_lshlrev_b32_e32 v52, 16, v101
	v_and_b32_e32 v53, 0xffff0000, v101
	v_pk_mul_f32 v[56:57], v[50:51], v[52:53]
	v_lshl_add_u64 v[50:51], s[34:35], 0, v[96:97]
	v_lshl_add_u64 v[50:51], v[50:51], 0, s[0:1]
	v_cvt_pk_bf16_f32 v52, v102, v103
	v_cvt_pk_bf16_f32 v53, v98, v99
	v_cvt_pk_bf16_f32 v54, v54, v55
	v_cvt_pk_bf16_f32 v55, v56, v57
	v_lshl_add_u64 v[50:51], v[50:51], 0, v[0:1]
	v_permlane32_swap_b32_e32 v52, v54
	v_permlane32_swap_b32_e32 v53, v55
	global_store_dwordx4 v[50:51], v[52:55], off offset:2048
	s_waitcnt vmcnt(14)
	v_lshlrev_b32_e32 v56, 16, v95
	v_and_b32_e32 v57, 0xffff0000, v95
	v_pk_mul_f32 v[52:53], v[58:59], v[68:69] op_sel_hi:[1,0]
	v_lshlrev_b32_e32 v54, 16, v94
	v_and_b32_e32 v55, 0xffff0000, v94
	v_pk_mul_f32 v[52:53], v[52:53], v[54:55]
	v_pk_mul_f32 v[54:55], v[60:61], v[68:69] op_sel_hi:[1,0]
	s_waitcnt vmcnt(13)
	v_lshlrev_b32_e32 v58, 16, v92
	v_pk_mul_f32 v[54:55], v[54:55], v[56:57]
	v_pk_mul_f32 v[56:57], v[62:63], v[68:69] op_sel_hi:[1,0]
	v_and_b32_e32 v59, 0xffff0000, v92
	v_pk_mul_f32 v[56:57], v[56:57], v[58:59]
	v_pk_mul_f32 v[58:59], v[64:65], v[68:69] op_sel_hi:[1,0]
	v_lshlrev_b32_e32 v60, 16, v93
	v_and_b32_e32 v61, 0xffff0000, v93
	v_pk_mul_f32 v[58:59], v[58:59], v[60:61]
	v_cvt_pk_bf16_f32 v52, v52, v53
	v_cvt_pk_bf16_f32 v53, v54, v55
	v_cvt_pk_bf16_f32 v54, v56, v57
	v_cvt_pk_bf16_f32 v55, v58, v59
	s_nop 0
	v_permlane32_swap_b32_e32 v52, v54
	v_permlane32_swap_b32_e32 v53, v55
	global_store_dwordx4 v[50:51], v[52:55], off offset:2080
	s_waitcnt vmcnt(13)
	s_nop 0
	v_lshlrev_b32_e32 v52, 16, v90
	v_and_b32_e32 v53, 0xffff0000, v90
	v_pk_mul_f32 v[34:35], v[34:35], v[52:53]
	v_lshlrev_b32_e32 v52, 16, v91
	v_and_b32_e32 v53, 0xffff0000, v91
	v_pk_mul_f32 v[36:37], v[36:37], v[52:53]
	s_waitcnt vmcnt(12)
; DI float bf_lo(unsigned u) { return __uint_as_float(u << 16); }
; DI float bf_hi(unsigned u) { return __uint_as_float(u & 0xffff0000u); }
; DI void mla_unit(const Params& p, const int t, int l, int h, int qb, char* lds) {
;     ...
;   for (int dt = 0; dt < 4; ++dt)
; #pragma unroll
;     for (int a = 0; a < 2; ++a) {
;       float xy[2][4];
; #pragma unroll
;       for (int q2 = 0; q2 < 2; ++q2) {
;         const int g = 2 * a + q2;
;         const u32x2 z = zv[dt * 4 + g];
;         xy[q2][0] = o[dt][4 * g] * inv * bf_lo(z[0]); xy[q2][1] = o[dt][4 * g + 1] * inv * bf_hi(z[0]);
;         xy[q2][2] = o[dt][4 * g + 2] * inv * bf_lo(z[1]); xy[q2][3] = o[dt][4 * g + 3] * inv * bf_hi(z[1]);
;       }
;       st8_pair_bf16(p.MIX + (size_t)qrow * 2048 + 1024 + h * 128 + 32 * dt + 16 * a + 8 * hf, xy[0], xy[1]);
;     }
	v_lshlrev_b32_e32 v52, 16, v88
	v_and_b32_e32 v53, 0xffff0000, v88
	v_pk_mul_f32 v[38:39], v[38:39], v[52:53]
	v_lshlrev_b32_e32 v52, 16, v89
	v_and_b32_e32 v53, 0xffff0000, v89
	v_pk_mul_f32 v[40:41], v[40:41], v[52:53]
	v_cvt_pk_bf16_f32 v34, v34, v35
	v_cvt_pk_bf16_f32 v35, v36, v37
	v_cvt_pk_bf16_f32 v36, v38, v39
	v_cvt_pk_bf16_f32 v37, v40, v41
	s_nop 0
	v_permlane32_swap_b32_e32 v34, v36
	v_permlane32_swap_b32_e32 v35, v37
	global_store_dwordx4 v[50:51], v[34:37], off offset:2112
	s_waitcnt vmcnt(12)
	v_lshlrev_b32_e32 v38, 16, v87
	v_and_b32_e32 v39, 0xffff0000, v87
	v_pk_mul_f32 v[34:35], v[42:43], v[68:69] op_sel_hi:[1,0]
	v_lshlrev_b32_e32 v36, 16, v86
	v_and_b32_e32 v37, 0xffff0000, v86
	v_pk_mul_f32 v[34:35], v[34:35], v[36:37]
	v_pk_mul_f32 v[36:37], v[44:45], v[68:69] op_sel_hi:[1,0]
	s_waitcnt vmcnt(11)
	v_lshlrev_b32_e32 v40, 16, v84
	v_pk_mul_f32 v[36:37], v[36:37], v[38:39]
	v_pk_mul_f32 v[38:39], v[46:47], v[68:69] op_sel_hi:[1,0]
	v_and_b32_e32 v41, 0xffff0000, v84
	v_pk_mul_f32 v[38:39], v[38:39], v[40:41]
	v_pk_mul_f32 v[40:41], v[48:49], v[68:69] op_sel_hi:[1,0]
	v_lshlrev_b32_e32 v42, 16, v85
	v_and_b32_e32 v43, 0xffff0000, v85
	v_pk_mul_f32 v[40:41], v[40:41], v[42:43]
	v_cvt_pk_bf16_f32 v34, v34, v35
	v_cvt_pk_bf16_f32 v35, v36, v37
	v_cvt_pk_bf16_f32 v36, v38, v39
	v_cvt_pk_bf16_f32 v37, v40, v41
	s_nop 0
	v_permlane32_swap_b32_e32 v34, v36
	v_permlane32_swap_b32_e32 v35, v37
	global_store_dwordx4 v[50:51], v[34:37], off offset:2144
	s_waitcnt vmcnt(11)
	s_nop 0
	v_lshlrev_b32_e32 v34, 16, v82
	v_and_b32_e32 v35, 0xffff0000, v82
	v_pk_mul_f32 v[18:19], v[18:19], v[34:35]
	v_lshlrev_b32_e32 v34, 16, v83
	v_and_b32_e32 v35, 0xffff0000, v83
	v_pk_mul_f32 v[20:21], v[20:21], v[34:35]
	s_waitcnt vmcnt(10)
	v_lshlrev_b32_e32 v34, 16, v80
	v_and_b32_e32 v35, 0xffff0000, v80
	v_pk_mul_f32 v[22:23], v[22:23], v[34:35]
	v_lshlrev_b32_e32 v34, 16, v81
	v_and_b32_e32 v35, 0xffff0000, v81
	v_pk_mul_f32 v[24:25], v[24:25], v[34:35]
	v_cvt_pk_bf16_f32 v18, v18, v19
	v_cvt_pk_bf16_f32 v19, v20, v21
	v_cvt_pk_bf16_f32 v20, v22, v23
	v_cvt_pk_bf16_f32 v21, v24, v25
	s_nop 0
	v_permlane32_swap_b32_e32 v18, v20
	v_permlane32_swap_b32_e32 v19, v21
	global_store_dwordx4 v[50:51], v[18:21], off offset:2176
	s_waitcnt vmcnt(10)
	v_lshlrev_b32_e32 v22, 16, v79
	v_and_b32_e32 v23, 0xffff0000, v79
	v_pk_mul_f32 v[18:19], v[26:27], v[68:69] op_sel_hi:[1,0]
	v_lshlrev_b32_e32 v20, 16, v78
	v_and_b32_e32 v21, 0xffff0000, v78
	v_pk_mul_f32 v[18:19], v[18:19], v[20:21]
	v_pk_mul_f32 v[20:21], v[28:29], v[68:69] op_sel_hi:[1,0]
	s_waitcnt vmcnt(9)
	v_lshlrev_b32_e32 v24, 16, v76
	v_pk_mul_f32 v[20:21], v[20:21], v[22:23]
	v_pk_mul_f32 v[22:23], v[30:31], v[68:69] op_sel_hi:[1,0]
	v_and_b32_e32 v25, 0xffff0000, v76
	v_pk_mul_f32 v[22:23], v[22:23], v[24:25]
	v_pk_mul_f32 v[24:25], v[32:33], v[68:69] op_sel_hi:[1,0]
	v_lshlrev_b32_e32 v26, 16, v77
	v_and_b32_e32 v27, 0xffff0000, v77
	v_pk_mul_f32 v[24:25], v[24:25], v[26:27]
	v_cvt_pk_bf16_f32 v18, v18, v19
	v_cvt_pk_bf16_f32 v19, v20, v21
	v_cvt_pk_bf16_f32 v20, v22, v23
	v_cvt_pk_bf16_f32 v21, v24, v25
	s_nop 0
	v_permlane32_swap_b32_e32 v18, v20
	v_permlane32_swap_b32_e32 v19, v21
	global_store_dwordx4 v[50:51], v[18:21], off offset:2208
	s_waitcnt vmcnt(9)
	s_nop 0
	v_lshlrev_b32_e32 v18, 16, v74
	v_and_b32_e32 v19, 0xffff0000, v74
	v_pk_mul_f32 v[2:3], v[2:3], v[18:19]
	v_lshlrev_b32_e32 v18, 16, v75
	v_and_b32_e32 v19, 0xffff0000, v75
	v_pk_mul_f32 v[4:5], v[4:5], v[18:19]
	s_waitcnt vmcnt(8)
	v_lshlrev_b32_e32 v18, 16, v72
	v_and_b32_e32 v19, 0xffff0000, v72
	v_pk_mul_f32 v[6:7], v[6:7], v[18:19]
	v_lshlrev_b32_e32 v18, 16, v73
	v_and_b32_e32 v19, 0xffff0000, v73
	v_pk_mul_f32 v[8:9], v[8:9], v[18:19]
	v_cvt_pk_bf16_f32 v2, v2, v3
	v_cvt_pk_bf16_f32 v3, v4, v5
	v_cvt_pk_bf16_f32 v4, v6, v7
	v_cvt_pk_bf16_f32 v5, v8, v9
	s_nop 0
	v_permlane32_swap_b32_e32 v2, v4
	v_permlane32_swap_b32_e32 v3, v5
	global_store_dwordx4 v[50:51], v[2:5], off offset:2240
	s_waitcnt vmcnt(8)
	v_lshlrev_b32_e32 v6, 16, v71
	v_and_b32_e32 v7, 0xffff0000, v71
	v_pk_mul_f32 v[2:3], v[10:11], v[68:69] op_sel_hi:[1,0]
	v_lshlrev_b32_e32 v4, 16, v70
	v_and_b32_e32 v5, 0xffff0000, v70
	v_pk_mul_f32 v[2:3], v[2:3], v[4:5]
	v_pk_mul_f32 v[4:5], v[12:13], v[68:69] op_sel_hi:[1,0]
	s_waitcnt vmcnt(7)
	v_lshlrev_b32_e32 v8, 16, v66
	v_pk_mul_f32 v[4:5], v[4:5], v[6:7]
	v_pk_mul_f32 v[6:7], v[14:15], v[68:69] op_sel_hi:[1,0]
	v_and_b32_e32 v9, 0xffff0000, v66
	v_pk_mul_f32 v[6:7], v[6:7], v[8:9]
	v_pk_mul_f32 v[8:9], v[16:17], v[68:69] op_sel_hi:[1,0]
	v_lshlrev_b32_e32 v10, 16, v67
	v_and_b32_e32 v11, 0xffff0000, v67
	v_pk_mul_f32 v[8:9], v[8:9], v[10:11]
	v_cvt_pk_bf16_f32 v2, v2, v3
	v_cvt_pk_bf16_f32 v3, v4, v5
	v_cvt_pk_bf16_f32 v4, v6, v7
	v_cvt_pk_bf16_f32 v5, v8, v9
	s_nop 0
	v_permlane32_swap_b32_e32 v2, v4
	v_permlane32_swap_b32_e32 v3, v5
	global_store_dwordx4 v[50:51], v[2:5], off offset:2272

; #define AT_LOAD(TT) do { const u16* kn_ = Kp + (size_t)((TT) << 6) * ldk; const u16* vn_ = Vt + ((TT) << 6); \
;     _Pragma("unroll") for (int pi = 0; pi < 2; ++pi) vr[pi] = *(const u32x4*)(vn_ + (size_t)64 * pi * S + voff); \
;     _Pragma("unroll") for (int pi = 0; pi < NKC; ++pi) kr[pi] = *(const u32x4*)(kn_ + 64 * pi + koff); } while (0)
; template <int DQK, int KROW, bool BIAS, bool MAPS2>
; DI void attn_core(const int t, const u16* __restrict__ Q, int ldq, const u16* __restrict__ Kp, int ldk, const u16* __restrict__ Vt, int q0,
;                   char* lds, const float* lut, float b31, f32x16 (&o)[4], float& l_out) {
;     ...
;   bf16x8 qf[NKS];
; #pragma unroll
;   for (int ks = 0; ks < NKS; ++ks) qf[ks] = *(const bf16x8*)(Q + (size_t)qrow * ldq + map * DQK + 16 * ks + 8 * hf);
; #pragma unroll
;   for (int dt = 0; dt < 4; ++dt)
; #pragma unroll
;     for (int i = 0; i < 16; ++i) o[dt][i] = 0.f;
;   float m_run = 0.f, l_run = 0.f;
;   const int ntile = (q0 >> 6) + (MAPS2 ? 2 : 4);
;   u32x4 kr[NKC], vr[2];
;   const unsigned koff = (unsigned)(t >> 3) * (unsigned)ldk + (unsigned)(t & 7) * 8u;
;   const unsigned voff = (unsigned)(t >> 3) * (unsigned)S + (unsigned)(t & 7) * 8u;
;   char* const klds = lds + (t >> 3) * KS + (t & 7) * 16;
;   char* const vlds = lds + AT_VOFF + (t >> 3) * VS + ((t & 7) >> 1) * 32 + (t & 1) * 8;
;     ...
;   AT_LOAD(0);
;   __syncthreads();
;   AT_WRITE(0);
;   AT_LOAD(1);
;   __syncthreads();
.LBB0_252:
	s_and_b64 vcc, exec, s[0:1]
	s_cbranch_vccz .LBB0_265
	s_lshl_b32 s0, s2, 8
	s_mul_i32 s4, s62, 0xc0
	s_sub_i32 s2, 0x1400, s0
	s_lshl_b64 s[0:1], s[4:5], 1
	s_add_u32 s90, s24, s0
	s_addc_u32 s91, s25, s1
	s_add_u32 s0, s22, s0
	v_ashrrev_i32_e32 v0, 1, v233
	s_addc_u32 s1, s23, s1
	s_lshl_b32 s88, s62, 7
	s_mov_b32 s89, s5
	v_and_b32_e32 v0, 0xffffffe0, v0
	s_lshl_b64 s[92:93], s[88:89], 14
	v_and_b32_e32 v29, 7, v233
	v_add_u32_e32 v167, s2, v0
	s_add_u32 s92, s26, s92
	v_ashrrev_i32_e32 v28, 3, v233
	v_lshlrev_b32_e32 v0, 3, v29
	v_and_b32_e32 v26, 31, v233
	s_addc_u32 s93, s27, s93
	v_lshl_or_b32 v2, v28, 13, v0
	v_mov_b32_e32 v3, v1
	v_mul_lo_u32 v6, v28, s72
	v_bfe_u32 v27, v233, 5, 1
	v_lshl_add_u64 v[168:169], v[2:3], 1, s[92:93]
	v_or_b32_e32 v6, v6, v0
	v_mov_b32_e32 v7, v1
	v_or_b32_e32 v170, v167, v26
	v_mov_b64_e32 v[24:25], s[90:91]
	v_lshl_add_u64 v[172:173], v[6:7], 1, s[0:1]
	v_add_co_u32_e32 v22, vcc, s74, v168
	v_mad_i64_i32 v[24:25], s[0:1], v170, s99, v[24:25]
	v_lshlrev_b32_e32 v0, 4, v27
	v_addc_co_u32_e32 v23, vcc, 0, v169, vcc
	v_lshl_add_u64 v[24:25], v[24:25], 0, v[0:1]
	global_load_dwordx4 v[2:5], v[168:169], off
	global_load_dwordx4 v[6:9], v[172:173], off
	global_load_dwordx4 v[10:13], v[172:173], off offset:128
	global_load_dwordx4 v[14:17], v[172:173], off offset:256
	global_load_dwordx4 v[18:21], v[22:23], off
	global_load_dwordx4 v[98:101], v[24:25], off
	global_load_dwordx4 v[102:105], v[24:25], off offset:32
	global_load_dwordx4 v[106:109], v[24:25], off offset:64
	global_load_dwordx4 v[110:113], v[24:25], off offset:96
	global_load_dwordx4 v[114:117], v[24:25], off offset:128
	global_load_dwordx4 v[118:121], v[24:25], off offset:160
	global_load_dwordx4 v[122:125], v[24:25], off offset:192
	global_load_dwordx4 v[126:129], v[24:25], off offset:224
	global_load_dwordx4 v[130:133], v[24:25], off offset:256
	global_load_dwordx4 v[134:137], v[24:25], off offset:288
	global_load_dwordx4 v[138:141], v[24:25], off offset:320
	global_load_dwordx4 v[142:145], v[24:25], off offset:352
	v_add_co_u32_e32 v24, vcc, s59, v172
	s_mov_b64 s[0:1], 0x30000
	s_nop 0
	v_addc_co_u32_e32 v25, vcc, 0, v173, vcc
	s_barrier
	global_load_dwordx4 v[146:149], v[168:169], off offset:128
	global_load_dwordx4 v[150:153], v[22:23], off offset:128
	v_lshl_add_u64 v[22:23], v[172:173], 0, s[0:1]
	global_load_dwordx4 v[154:157], v[24:25], off
	global_load_dwordx4 v[158:161], v[22:23], off offset:128
	global_load_dwordx4 v[162:165], v[22:23], off offset:256
	v_mul_lo_u32 v23, v28, s75
	v_lshlrev_b32_e32 v24, 4, v29
	v_lshlrev_b32_e32 v25, 8, v28
	v_and_b32_e32 v28, 0x60, v24
	v_sub_u32_e32 v25, v23, v25
	v_lshlrev_b32_e32 v22, 3, v233
	v_add_u32_e32 v174, v23, v24
	v_add_u32_e32 v23, v25, v28
	v_and_or_b32 v175, v22, 8, v23
	v_add_u32_e32 v22, 0xc800, v175
	v_add_u32_e32 v23, 0xe800, v175
	v_mad_u32_u24 v178, v26, s75, v0
	v_lshlrev_b32_e32 v0, 8, v26
	v_lshlrev_b32_e32 v166, 3, v27
	v_lshlrev_b32_e32 v176, 2, v27
	v_sub_u32_e32 v179, v178, v0
	v_mov_b32_e32 v0, v1
	s_lshr_b32 s2, s2, 6
	s_mov_b32 s93, 0
	v_ashrrev_i32_e32 v171, 31, v170
	s_add_i32 s2, s2, 4
	v_or_b32_e32 v177, 31, v167
	v_mov_b32_e32 v180, 0
	s_movk_i32 s4, 0x80
	s_waitcnt vmcnt(20)
	ds_write_b128 v174, v[6:9]
	s_waitcnt vmcnt(19)
	ds_write_b128 v174, v[10:13] offset:128
	s_waitcnt vmcnt(18)
	ds_write_b128 v174, v[14:17] offset:256
	ds_write2_b64 v22, v[2:3], v[4:5] offset1:2
	s_waitcnt vmcnt(17)
	ds_write2_b64 v23, v[18:19], v[20:21] offset0:128 offset1:130
	v_mov_b32_e32 v14, v1
	v_mov_b32_e32 v15, v1
	v_mov_b32_e32 v2, v1
	v_mov_b32_e32 v3, v1
	v_mov_b32_e32 v4, v1
	v_mov_b32_e32 v5, v1
	v_mov_b32_e32 v6, v1
	v_mov_b32_e32 v7, v1
	v_mov_b32_e32 v8, v1
	v_mov_b32_e32 v9, v1
	v_mov_b32_e32 v10, v1
	v_mov_b32_e32 v11, v1
	v_mov_b32_e32 v12, v1
	v_mov_b32_e32 v13, v1
	v_mov_b64_e32 v[64:65], v[14:15]
	v_mov_b64_e32 v[48:49], v[14:15]
	v_mov_b64_e32 v[32:33], v[14:15]
	v_mov_b64_e32 v[62:63], v[12:13]
	v_mov_b64_e32 v[60:61], v[10:11]
	v_mov_b64_e32 v[58:59], v[8:9]
	v_mov_b64_e32 v[56:57], v[6:7]
	v_mov_b64_e32 v[54:55], v[4:5]
	v_mov_b64_e32 v[52:53], v[2:3]
	v_mov_b64_e32 v[50:51], v[0:1]
	v_mov_b64_e32 v[46:47], v[12:13]
	v_mov_b64_e32 v[44:45], v[10:11]
	v_mov_b64_e32 v[42:43], v[8:9]
	v_mov_b64_e32 v[40:41], v[6:7]
	v_mov_b64_e32 v[38:39], v[4:5]
	v_mov_b64_e32 v[36:37], v[2:3]
	v_mov_b64_e32 v[34:35], v[0:1]
	v_mov_b64_e32 v[30:31], v[12:13]
	v_mov_b64_e32 v[28:29], v[10:11]
	v_mov_b64_e32 v[26:27], v[8:9]
	v_mov_b64_e32 v[24:25], v[6:7]
	v_mov_b64_e32 v[22:23], v[4:5]
	v_mov_b64_e32 v[20:21], v[2:3]
	v_mov_b64_e32 v[18:19], v[0:1]
	v_mov_b64_e32 v[16:17], v[14:15]
	v_mov_b64_e32 v[14:15], v[12:13]
	v_mov_b64_e32 v[12:13], v[10:11]
	v_mov_b64_e32 v[10:11], v[8:9]
	v_mov_b64_e32 v[8:9], v[6:7]
	v_mov_b64_e32 v[6:7], v[4:5]
	v_mov_b64_e32 v[4:5], v[2:3]
	v_mov_b64_e32 v[2:3], v[0:1]
	v_mov_b32_e32 v0, 0
	s_waitcnt lgkmcnt(0)
	s_barrier
	v_readfirstlane_b32 s100, v233
	s_nop 3
	s_cmp_lt_u32 s100, 0x100
	s_cbranch_scc1 .Lsp_2
	s_setprio 1
.Lsp_2:
	s_add_i32 s53, s93, 1
	s_cmp_ge_u32 s53, s2
	s_cbranch_scc1 .LBB0_256

; #define MFMA32(a, b, c) __builtin_amdgcn_mfma_f32_32x32x16_bf16((a), (b), (c), 0, 0, 0)
; template <int DQK, int KROW, bool BIAS, bool MAPS2>
; DI void attn_core(const int t, const u16* __restrict__ Q, int ldq, const u16* __restrict__ Kp, int ldk, const u16* __restrict__ Vt, int q0,
;                   char* lds, const float* lut, float b31, f32x16 (&o)[4], float& l_out) {
;     ...
;     const bool live = (kt << 6) <= wq0 + 31;
;     if (live) {
;       const int k0 = kt << 6;
;       const bool far = BIAS && (wq0 - (k0 + 63) >= 128);
;       const float init = (far ? b31 : 0.f) - m_run;
; #pragma unroll
;       for (int k2 = 0; k2 < 2; ++k2)
; #pragma unroll
;         for (int i = 0; i < 16; ++i) s[k2][i] = init;
;       {
;         constexpr int QBS = (NKS > 4) ? 2 : 4, NBT = NKS / QBS;
;         bf16x8 kfb[2][QBS][2];
;         const char* kbase = lds + (kt & 1) * AT_KBUF + r * KS + hf * 16 + map * (DQK * 2);
; #pragma unroll
;         for (int jq = 0; jq < QBS; ++jq)
; #pragma unroll
;           for (int k2 = 0; k2 < 2; ++k2) kfb[0][jq][k2] = *(const bf16x8*)(kbase + 32 * k2 * KS + jq * 32);
; #pragma unroll
;         for (int b = 0; b < NBT; ++b) {
;           if (b + 1 < NBT) {
; #pragma unroll
;             for (int jq = 0; jq < QBS; ++jq)
; #pragma unroll
;               for (int k2 = 0; k2 < 2; ++k2) kfb[(b + 1) & 1][jq][k2] = *(const bf16x8*)(kbase + 32 * k2 * KS + ((b + 1) * QBS + jq) * 32);
;           }
;           __builtin_amdgcn_sched_barrier(0);
;           __builtin_amdgcn_s_setprio(1);
; #pragma unroll
;           for (int jq = 0; jq < QBS; ++jq)
; #pragma unroll
;             for (int k2 = 0; k2 < 2; ++k2) s[k2] = MFMA32(kfb[b & 1][jq][k2], qf[b * QBS + jq], s[k2]);
;           __builtin_amdgcn_s_setprio(0);
;           __builtin_amdgcn_sched_barrier(0);
;         }
.LBB0_256:
	s_add_i32 s0, s4, 0xffffff80
	v_cmp_le_i32_e32 vcc, s0, v177
	s_and_saveexec_b64 s[90:91], vcc
	s_cbranch_execz .LBB0_262
	s_and_b32 s92, s93, 1
	s_mul_i32 s0, s92, 0x6400
	v_add_u32_e32 v181, s0, v178
	ds_read_b128 v[182:185], v181
	ds_read_b128 v[186:189], v181 offset:32
	ds_read_b128 v[190:193], v181 offset:12800
	ds_read_b128 v[194:197], v181 offset:12832
	ds_read_b128 v[198:201], v181 offset:64
	ds_read_b128 v[202:205], v181 offset:96
	ds_read_b128 v[206:209], v181 offset:12864
	ds_read_b128 v[210:213], v181 offset:12896
	v_sub_f32_e32 v66, 0, v180
	v_mov_b32_e32 v67, v66
	v_mov_b32_e32 v68, v66
	v_mov_b32_e32 v69, v66
	v_mov_b32_e32 v70, v66
	v_mov_b32_e32 v71, v66
	v_mov_b32_e32 v72, v66
	v_mov_b32_e32 v73, v66
	v_mov_b32_e32 v74, v66
	v_mov_b32_e32 v75, v66
	v_mov_b32_e32 v76, v66
	v_mov_b32_e32 v77, v66
	v_mov_b32_e32 v78, v66
	v_mov_b32_e32 v79, v66
	v_mov_b32_e32 v80, v66
	v_mov_b32_e32 v81, v66
	s_waitcnt vmcnt(16) lgkmcnt(7)
	s_nop 0
	v_mfma_f32_32x32x16_bf16 v[82:97], v[182:185], v[98:101], v[66:81]
	s_waitcnt lgkmcnt(5)
	v_mfma_f32_32x32x16_bf16 v[66:81], v[190:193], v[98:101], v[66:81]
	s_waitcnt vmcnt(15)
	v_mfma_f32_32x32x16_bf16 v[82:97], v[186:189], v[102:105], v[82:97]
	s_waitcnt lgkmcnt(4)
	v_mfma_f32_32x32x16_bf16 v[66:81], v[194:197], v[102:105], v[66:81]
	ds_read_b128 v[182:185], v181 offset:128
	ds_read_b128 v[186:189], v181 offset:160
	ds_read_b128 v[190:193], v181 offset:12928
	ds_read_b128 v[194:197], v181 offset:12960
	s_waitcnt vmcnt(14) lgkmcnt(7)
	v_mfma_f32_32x32x16_bf16 v[82:97], v[198:201], v[106:109], v[82:97]
	s_waitcnt lgkmcnt(5)
	v_mfma_f32_32x32x16_bf16 v[66:81], v[206:209], v[106:109], v[66:81]
	s_waitcnt vmcnt(13)
	v_mfma_f32_32x32x16_bf16 v[82:97], v[202:205], v[110:113], v[82:97]
	s_waitcnt lgkmcnt(4)
	v_mfma_f32_32x32x16_bf16 v[66:81], v[210:213], v[110:113], v[66:81]
	ds_read_b128 v[198:201], v181 offset:192
	ds_read_b128 v[202:205], v181 offset:224
	ds_read_b128 v[206:209], v181 offset:12992
	ds_read_b128 v[210:213], v181 offset:13024
	s_waitcnt vmcnt(12) lgkmcnt(7)
	v_mfma_f32_32x32x16_bf16 v[82:97], v[182:185], v[114:117], v[82:97]
	s_waitcnt lgkmcnt(5)
	v_mfma_f32_32x32x16_bf16 v[66:81], v[190:193], v[114:117], v[66:81]
	s_waitcnt vmcnt(11)
	v_mfma_f32_32x32x16_bf16 v[82:97], v[186:189], v[118:121], v[82:97]
	s_waitcnt lgkmcnt(4)
	v_mfma_f32_32x32x16_bf16 v[66:81], v[194:197], v[118:121], v[66:81]
	ds_read_b128 v[182:185], v181 offset:256
	ds_read_b128 v[186:189], v181 offset:288
	ds_read_b128 v[190:193], v181 offset:13056
	ds_read_b128 v[194:197], v181 offset:13088
	s_waitcnt vmcnt(10) lgkmcnt(7)
	v_mfma_f32_32x32x16_bf16 v[82:97], v[198:201], v[122:125], v[82:97]
	s_waitcnt lgkmcnt(5)
	v_mfma_f32_32x32x16_bf16 v[66:81], v[206:209], v[122:125], v[66:81]
	s_waitcnt vmcnt(9)
	v_mfma_f32_32x32x16_bf16 v[82:97], v[202:205], v[126:129], v[82:97]
	s_waitcnt lgkmcnt(4)
	v_mfma_f32_32x32x16_bf16 v[66:81], v[210:213], v[126:129], v[66:81]
	ds_read_b128 v[198:201], v181 offset:320
	ds_read_b128 v[202:205], v181 offset:352
	ds_read_b128 v[206:209], v181 offset:13120
	ds_read_b128 v[210:213], v181 offset:13152
	s_waitcnt vmcnt(8) lgkmcnt(7)
	v_mfma_f32_32x32x16_bf16 v[82:97], v[182:185], v[130:133], v[82:97]
	s_waitcnt lgkmcnt(5)
	v_mfma_f32_32x32x16_bf16 v[66:81], v[190:193], v[130:133], v[66:81]
	s_waitcnt vmcnt(7)
	v_mfma_f32_32x32x16_bf16 v[82:97], v[186:189], v[134:137], v[82:97]
	s_waitcnt lgkmcnt(4)
	v_mfma_f32_32x32x16_bf16 v[66:81], v[194:197], v[134:137], v[66:81]
	s_waitcnt vmcnt(6) lgkmcnt(3)
	v_mfma_f32_32x32x16_bf16 v[82:97], v[198:201], v[138:141], v[82:97]
	s_waitcnt lgkmcnt(1)
	v_mfma_f32_32x32x16_bf16 v[66:81], v[206:209], v[138:141], v[66:81]
	s_waitcnt vmcnt(5)
	v_mfma_f32_32x32x16_bf16 v[82:97], v[202:205], v[142:145], v[82:97]
	s_waitcnt lgkmcnt(0)
	v_mfma_f32_32x32x16_bf16 v[66:81], v[210:213], v[142:145], v[66:81]
	s_add_i32 s0, s4, 0xffffffbf
	v_cmp_gt_i32_e32 vcc, s0, v167
	s_and_saveexec_b64 s[0:1], vcc
	s_cbranch_execz .LBB0_259
; template <int DQK, int KROW, bool BIAS, bool MAPS2>
; DI void attn_core(const int t, const u16* __restrict__ Q, int ldq, const u16* __restrict__ Kp, int ldk, const u16* __restrict__ Vt, int q0,
;                   char* lds, const float* lut, float b31, f32x16 (&o)[4], float& l_out) {
;     ...
;       if (k0 + 63 > wq0) {
; #pragma unroll
;         for (int k2 = 0; k2 < 2; ++k2)
; #pragma unroll
;           for (int i = 0; i < 16; ++i) {
;             const int key = k0 + 32 * k2 + (i & 3) + 8 * (i >> 2) + 4 * hf;
;             if (key > qrow) s[k2][i] = -INFINITY;
;           }
;       }
	v_add_u32_e32 v181, s4, v176
	v_add_u32_e32 v182, 0xffffff80, v181
	v_cmp_gt_i32_e32 vcc, v182, v170
	s_nop 1
	v_cndmask_b32_e32 v183, v82, v230, vcc
	v_cmp_lt_i32_e32 vcc, v182, v170
	v_add_u32_e32 v182, 0xffffff82, v181
	s_nop 0
	v_cndmask_b32_e32 v82, v183, v82, vcc
	v_cndmask_b32_e32 v83, v230, v83, vcc
	v_cmp_le_i32_e32 vcc, v182, v170
	v_add_u32_e32 v182, 0xffffff83, v181
	s_nop 0
	v_cndmask_b32_e32 v84, v230, v84, vcc
	v_cmp_le_i32_e32 vcc, v182, v170
	v_add_u32_e32 v182, 0xffffff88, v181
	s_nop 0
	v_cndmask_b32_e32 v85, v230, v85, vcc
	v_cmp_le_i32_e32 vcc, v182, v170
	v_add_u32_e32 v182, 0xffffff89, v181
	s_nop 0
	v_cndmask_b32_e32 v86, v230, v86, vcc
	v_cmp_le_i32_e32 vcc, v182, v170
	v_add_u32_e32 v182, 0xffffff8a, v181
	s_nop 0
	v_cndmask_b32_e32 v87, v230, v87, vcc
	v_cmp_le_i32_e32 vcc, v182, v170
	v_add_u32_e32 v182, 0xffffff8b, v181
	s_nop 0
	v_cndmask_b32_e32 v88, v230, v88, vcc
	v_cmp_le_i32_e32 vcc, v182, v170
	v_add_u32_e32 v182, 0xffffff90, v181
	s_nop 0
	v_cndmask_b32_e32 v89, v230, v89, vcc
	v_cmp_le_i32_e32 vcc, v182, v170
	v_add_u32_e32 v182, 0xffffff91, v181
	s_nop 0
	v_cndmask_b32_e32 v90, v230, v90, vcc
	v_cmp_le_i32_e32 vcc, v182, v170
	v_add_u32_e32 v182, 0xffffff92, v181
	s_nop 0
	v_cndmask_b32_e32 v91, v230, v91, vcc
	v_cmp_le_i32_e32 vcc, v182, v170
	v_add_u32_e32 v182, 0xffffff93, v181
	s_nop 0
	v_cndmask_b32_e32 v92, v230, v92, vcc
	v_cmp_le_i32_e32 vcc, v182, v170
	v_add_u32_e32 v182, 0xffffff98, v181
	s_nop 0
	v_cndmask_b32_e32 v93, v230, v93, vcc
	v_cmp_le_i32_e32 vcc, v182, v170
	v_add_u32_e32 v182, 0xffffff99, v181
	s_nop 0
	v_cndmask_b32_e32 v94, v230, v94, vcc
	v_cmp_le_i32_e32 vcc, v182, v170
	v_add_u32_e32 v182, 0xffffff9a, v181
	s_nop 0
	v_cndmask_b32_e32 v95, v230, v95, vcc
	v_cmp_le_i32_e32 vcc, v182, v170
	v_add_u32_e32 v182, 0xffffff9b, v181
	s_nop 0
	v_cndmask_b32_e32 v96, v230, v96, vcc
	v_cmp_le_i32_e32 vcc, v182, v170
	v_add_u32_e32 v182, 0xffffffa0, v181
	s_nop 0
	v_cndmask_b32_e32 v97, v230, v97, vcc
	v_cmp_le_i32_e32 vcc, v182, v170
	v_add_u32_e32 v182, 0xffffffa1, v181
	s_nop 0
	v_cndmask_b32_e32 v66, v230, v66, vcc
	v_cmp_le_i32_e32 vcc, v182, v170
	v_add_u32_e32 v182, 0xffffffa2, v181
	s_nop 0
	v_cndmask_b32_e32 v67, v230, v67, vcc
	v_cmp_le_i32_e32 vcc, v182, v170
	v_add_u32_e32 v182, 0xffffffa3, v181
	s_nop 0
	v_cndmask_b32_e32 v68, v230, v68, vcc
	v_cmp_le_i32_e32 vcc, v182, v170
	v_add_u32_e32 v182, 0xffffffa8, v181
	s_nop 0
	v_cndmask_b32_e32 v69, v230, v69, vcc
	v_cmp_le_i32_e32 vcc, v182, v170
	v_add_u32_e32 v182, 0xffffffa9, v181
	s_nop 0
	v_cndmask_b32_e32 v70, v230, v70, vcc
	v_cmp_le_i32_e32 vcc, v182, v170
	v_add_u32_e32 v182, 0xffffffaa, v181
	s_nop 0
	v_cndmask_b32_e32 v71, v230, v71, vcc
	v_cmp_le_i32_e32 vcc, v182, v170
	v_add_u32_e32 v182, 0xffffffab, v181
	s_nop 0
	v_cndmask_b32_e32 v72, v230, v72, vcc
	v_cmp_le_i32_e32 vcc, v182, v170
	v_add_u32_e32 v182, 0xffffffb0, v181
	s_nop 0
	v_cndmask_b32_e32 v73, v230, v73, vcc
	v_cmp_le_i32_e32 vcc, v182, v170
	v_add_u32_e32 v182, 0xffffffb1, v181
	s_nop 0
	v_cndmask_b32_e32 v74, v230, v74, vcc
	v_cmp_le_i32_e32 vcc, v182, v170
	v_add_u32_e32 v182, 0xffffffb2, v181
	s_nop 0
	v_cndmask_b32_e32 v75, v230, v75, vcc
	v_cmp_le_i32_e32 vcc, v182, v170
	v_add_u32_e32 v182, 0xffffffb3, v181
	s_nop 0
	v_cndmask_b32_e32 v76, v230, v76, vcc
	v_cmp_le_i32_e32 vcc, v182, v170
	v_add_u32_e32 v182, 0xffffffb8, v181
	s_nop 0
	v_cndmask_b32_e32 v77, v230, v77, vcc
	v_cmp_le_i32_e32 vcc, v182, v170
	v_add_u32_e32 v182, 0xffffffb9, v181
	s_nop 0
	v_cndmask_b32_e32 v78, v230, v78, vcc
	v_cmp_le_i32_e32 vcc, v182, v170
	v_add_u32_e32 v182, 0xffffffba, v181
	v_add_u32_e32 v181, 0xffffffbb, v181
	v_cndmask_b32_e32 v79, v230, v79, vcc
	v_cmp_le_i32_e32 vcc, v182, v170
	s_nop 1
	v_cndmask_b32_e32 v80, v230, v80, vcc
	v_cmp_le_i32_e32 vcc, v181, v170
	s_nop 1
	v_cndmask_b32_e32 v81, v230, v81, vcc

; #define MFMA32(a, b, c) __builtin_amdgcn_mfma_f32_32x32x16_bf16((a), (b), (c), 0, 0, 0)
; template <int DQK, int KROW, bool BIAS, bool MAPS2>
; DI void attn_core(const int t, const u16* __restrict__ Q, int ldq, const u16* __restrict__ Kp, int ldk, const u16* __restrict__ Vt, int q0,
;                   char* lds, const float* lut, float b31, f32x16 (&o)[4], float& l_out) {
;     ...
;       float ps = 0.f;
; #pragma unroll
;       for (int k2 = 0; k2 < 2; ++k2)
; #pragma unroll
;         for (int i = 0; i < 16; ++i) { const float pv = __builtin_amdgcn_exp2f(s[k2][i]); s[k2][i] = pv; ps += pv; }
;       l_run += ps;
;       bf16x8 vfb[2][4];
;       const char* vbase = lds + AT_VOFF + (kt & 1) * AT_VBUF + r * VS + hf * 16;
; #pragma unroll
;       for (int dt = 0; dt < 4; ++dt) vfb[0][dt] = *(const bf16x8*)(vbase + 32 * dt * VS);
; #pragma unroll
;       for (int bb = 0; bb < 4; ++bb) {
;         const int k2 = bb >> 1, s2 = bb & 1;
;         if (bb + 1 < 4) {
; #pragma unroll
;           for (int dt = 0; dt < 4; ++dt) vfb[(bb + 1) & 1][dt] = *(const bf16x8*)(vbase + 32 * dt * VS + (bb + 1) * 32);
;         }
;         u32x4 pp;
;         pp[0] = pk_bf16(s[k2][8 * s2 + 0], s[k2][8 * s2 + 1]);
;         pp[1] = pk_bf16(s[k2][8 * s2 + 2], s[k2][8 * s2 + 3]);
;         pp[2] = pk_bf16(s[k2][8 * s2 + 4], s[k2][8 * s2 + 5]);
;         pp[3] = pk_bf16(s[k2][8 * s2 + 6], s[k2][8 * s2 + 7]);
;         const bf16x8 pf = __builtin_bit_cast(bf16x8, pp);
;         __builtin_amdgcn_sched_barrier(0);
;         __builtin_amdgcn_s_setprio(1);
; #pragma unroll
;         for (int dt = 0; dt < 4; ++dt) o[dt] = MFMA32(vfb[bb & 1][dt], pf, o[dt]);
;         __builtin_amdgcn_s_setprio(0);
;         __builtin_amdgcn_sched_barrier(0);
;       }
.LBB0_261:
	v_exp_f32_e32 v181, v82
	v_exp_f32_e32 v182, v83
	v_exp_f32_e32 v183, v84
	v_exp_f32_e32 v184, v85
	v_add_f32_e32 v82, 0, v181
	v_exp_f32_e32 v185, v86
	v_add_f32_e32 v82, v182, v82
	v_exp_f32_e32 v186, v87
	v_add_f32_e32 v82, v183, v82
	v_exp_f32_e32 v187, v88
	v_add_f32_e32 v82, v184, v82
	v_exp_f32_e32 v188, v89
	v_add_f32_e32 v82, v185, v82
	v_exp_f32_e32 v189, v90
	v_add_f32_e32 v82, v186, v82
	v_exp_f32_e32 v190, v91
	v_add_f32_e32 v82, v187, v82
	v_exp_f32_e32 v191, v92
	v_add_f32_e32 v82, v188, v82
	v_exp_f32_e32 v192, v93
	v_add_f32_e32 v82, v189, v82
	v_exp_f32_e32 v193, v94
	v_add_f32_e32 v82, v190, v82
	v_exp_f32_e32 v194, v95
	v_add_f32_e32 v82, v191, v82
	v_exp_f32_e32 v195, v96
	v_add_f32_e32 v82, v192, v82
	v_exp_f32_e32 v196, v97
	v_add_f32_e32 v82, v193, v82
	v_exp_f32_e32 v197, v66
	v_add_f32_e32 v82, v194, v82
	v_exp_f32_e32 v198, v67
	v_add_f32_e32 v82, v195, v82
	v_exp_f32_e32 v199, v68
	v_add_f32_e32 v82, v196, v82
	v_exp_f32_e32 v200, v69
	v_add_f32_e32 v66, v197, v82
	v_exp_f32_e32 v201, v70
	v_add_f32_e32 v66, v198, v66
	v_exp_f32_e32 v202, v71
	v_add_f32_e32 v66, v199, v66
	v_exp_f32_e32 v203, v72
	v_add_f32_e32 v66, v200, v66
	v_exp_f32_e32 v204, v73
	v_add_f32_e32 v66, v201, v66
	v_exp_f32_e32 v205, v74
	v_add_f32_e32 v66, v202, v66
	v_exp_f32_e32 v206, v75
	v_add_f32_e32 v66, v203, v66
	v_exp_f32_e32 v207, v76
	v_add_f32_e32 v66, v204, v66
	v_exp_f32_e32 v208, v77
	v_add_f32_e32 v66, v205, v66
	v_exp_f32_e32 v209, v78
	v_add_f32_e32 v66, v206, v66
	v_exp_f32_e32 v210, v79
	v_add_f32_e32 v66, v207, v66
	v_exp_f32_e32 v211, v80
	v_add_f32_e32 v66, v208, v66
	v_exp_f32_e32 v212, v81
	v_add_f32_e32 v66, v209, v66
	v_add_f32_e32 v66, v210, v66
	s_mulk_i32 s92, 0x4800
	v_add_f32_e32 v66, v211, v66
	v_add_u32_e32 v214, s92, v179
	v_add_f32_e32 v213, v212, v66
	ds_read_b128 v[66:69], v214 offset:51200
	ds_read_b128 v[70:73], v214 offset:51232
	ds_read_b128 v[74:77], v214 offset:55808
	ds_read_b128 v[78:81], v214 offset:55840
	ds_read_b128 v[82:85], v214 offset:60416
	ds_read_b128 v[86:89], v214 offset:60448
	ds_read_b128 v[90:93], v214 offset:65024
	ds_read_b128 v[94:97], v214 offset:65056
	v_cvt_pk_bf16_f32 v182, v181, v182
	v_cvt_pk_bf16_f32 v183, v183, v184
	v_cvt_pk_bf16_f32 v184, v185, v186
	v_cvt_pk_bf16_f32 v185, v187, v188
	s_waitcnt lgkmcnt(7)
	v_mfma_f32_32x32x16_bf16 v[50:65], v[66:69], v[182:185], v[50:65]
	s_waitcnt lgkmcnt(5)
	v_mfma_f32_32x32x16_bf16 v[34:49], v[74:77], v[182:185], v[34:49]
	s_waitcnt lgkmcnt(3)
	v_mfma_f32_32x32x16_bf16 v[18:33], v[82:85], v[182:185], v[18:33]
	s_waitcnt lgkmcnt(1)
	v_mfma_f32_32x32x16_bf16 v[2:17], v[90:93], v[182:185], v[2:17]
	ds_read_b128 v[66:69], v214 offset:51264
	ds_read_b128 v[74:77], v214 offset:55872
	ds_read_b128 v[82:85], v214 offset:60480
	ds_read_b128 v[90:93], v214 offset:65088
	v_cvt_pk_bf16_f32 v182, v189, v190
	v_cvt_pk_bf16_f32 v183, v191, v192
	v_cvt_pk_bf16_f32 v184, v193, v194
	v_cvt_pk_bf16_f32 v185, v195, v196
	s_nop 0
	v_mfma_f32_32x32x16_bf16 v[50:65], v[70:73], v[182:185], v[50:65]
	v_mfma_f32_32x32x16_bf16 v[34:49], v[78:81], v[182:185], v[34:49]
	v_mfma_f32_32x32x16_bf16 v[18:33], v[86:89], v[182:185], v[18:33]
	s_waitcnt lgkmcnt(4)
	v_mfma_f32_32x32x16_bf16 v[2:17], v[94:97], v[182:185], v[2:17]
	ds_read_b128 v[70:73], v214 offset:51296
	ds_read_b128 v[78:81], v214 offset:55904
	ds_read_b128 v[86:89], v214 offset:60512
	ds_read_b128 v[94:97], v214 offset:65120
	v_cvt_pk_bf16_f32 v182, v197, v198
	v_cvt_pk_bf16_f32 v183, v199, v200
	v_cvt_pk_bf16_f32 v184, v201, v202
	v_cvt_pk_bf16_f32 v185, v203, v204
	s_waitcnt lgkmcnt(7)
	v_mfma_f32_32x32x16_bf16 v[50:65], v[66:69], v[182:185], v[50:65]
	s_waitcnt lgkmcnt(6)
	v_mfma_f32_32x32x16_bf16 v[34:49], v[74:77], v[182:185], v[34:49]
	s_waitcnt lgkmcnt(5)
	v_mfma_f32_32x32x16_bf16 v[18:33], v[82:85], v[182:185], v[18:33]
	s_waitcnt lgkmcnt(4)
	v_mfma_f32_32x32x16_bf16 v[2:17], v[90:93], v[182:185], v[2:17]
	v_cvt_pk_bf16_f32 v66, v205, v206
	v_cvt_pk_bf16_f32 v67, v207, v208
	v_cvt_pk_bf16_f32 v68, v209, v210
	v_cvt_pk_bf16_f32 v69, v211, v212
	s_waitcnt lgkmcnt(3)
	v_mfma_f32_32x32x16_bf16 v[50:65], v[70:73], v[66:69], v[50:65]
	s_waitcnt lgkmcnt(2)
	v_mfma_f32_32x32x16_bf16 v[34:49], v[78:81], v[66:69], v[34:49]
	s_waitcnt lgkmcnt(1)
	v_mfma_f32_32x32x16_bf16 v[18:33], v[86:89], v[66:69], v[18:33]
	s_waitcnt lgkmcnt(0)
	v_mfma_f32_32x32x16_bf16 v[2:17], v[94:97], v[66:69], v[2:17]
	v_add_f32_e32 v0, v0, v213

; DI float bf_lo(unsigned u) { return __uint_as_float(u << 16); }
; DI float bf_hi(unsigned u) { return __uint_as_float(u & 0xffff0000u); }
; template <int DQK, int KROW, bool BIAS, bool MAPS2>
; DI void attn_core(const int t, const u16* __restrict__ Q, int ldq, const u16* __restrict__ Kp, int ldk, const u16* __restrict__ Vt, int q0,
;                   char* lds, const float* lut, float b31, f32x16 (&o)[4], float& l_out) {
;     ...
;   l_out = xhalf_sum(l_run);
; }
; DI void mla_unit(const Params& p, const int t, int l, int h, int qb, char* lds) {
;     ...
;   const float inv = 1.0f / lsum;
;   u32x2 zv[16];
; #pragma unroll
;   for (int dt = 0; dt < 4; ++dt)
; #pragma unroll
;     for (int g = 0; g < 4; ++g) zv[dt * 4 + g] = *(const u32x2*)(p.ZG + (size_t)qrow * 2048 + 1024 + h * 128 + 32 * dt + 8 * g + 4 * hf);
; #pragma unroll
;   for (int dt = 0; dt < 4; ++dt)
; #pragma unroll
;     for (int a = 0; a < 2; ++a) {
;       float xy[2][4];
; #pragma unroll
;       for (int q2 = 0; q2 < 2; ++q2) {
;         const int g = 2 * a + q2;
;         const u32x2 z = zv[dt * 4 + g];
;         xy[q2][0] = o[dt][4 * g] * inv * bf_lo(z[0]); xy[q2][1] = o[dt][4 * g + 1] * inv * bf_hi(z[0]);
;         xy[q2][2] = o[dt][4 * g + 2] * inv * bf_lo(z[1]); xy[q2][3] = o[dt][4 * g + 3] * inv * bf_hi(z[1]);
;       }
;       st8_pair_bf16(p.MIX + (size_t)qrow * 2048 + 1024 + h * 128 + 32 * dt + 16 * a + 8 * hf, xy[0], xy[1]);
;     }
.LBB0_264:
	s_setprio 0
	v_mov_b32_e32 v66, v0
	s_nop 1
	v_permlane32_swap_b32_e32 v0, v66
	v_lshlrev_b64 v[96:97], 12, v[170:171]
	v_add_f32_e32 v68, v0, v66
	v_lshl_add_u64 v[66:67], s[48:49], 0, v[96:97]
	s_lshl_b64 s[0:1], s[88:89], 1
	v_lshl_add_u64 v[66:67], v[66:67], 0, s[0:1]
	v_lshlrev_b32_e32 v0, 1, v176
	v_lshl_add_u64 v[66:67], v[66:67], 0, v[0:1]
	global_load_dwordx2 v[98:99], v[66:67], off offset:2048
	global_load_dwordx2 v[100:101], v[66:67], off offset:2064
	global_load_dwordx2 v[94:95], v[66:67], off offset:2080
	global_load_dwordx2 v[92:93], v[66:67], off offset:2096
	global_load_dwordx2 v[90:91], v[66:67], off offset:2112
	global_load_dwordx2 v[88:89], v[66:67], off offset:2128
	global_load_dwordx2 v[86:87], v[66:67], off offset:2144
	global_load_dwordx2 v[84:85], v[66:67], off offset:2160
	global_load_dwordx2 v[82:83], v[66:67], off offset:2176
	global_load_dwordx2 v[80:81], v[66:67], off offset:2192
	global_load_dwordx2 v[78:79], v[66:67], off offset:2208
	global_load_dwordx2 v[76:77], v[66:67], off offset:2224
	global_load_dwordx2 v[74:75], v[66:67], off offset:2240
	global_load_dwordx2 v[72:73], v[66:67], off offset:2256
	global_load_dwordx2 v[70:71], v[66:67], off offset:2272
	s_nop 0
	global_load_dwordx2 v[66:67], v[66:67], off offset:2288
	v_div_scale_f32 v0, s[88:89], v68, v68, 1.0
	v_rcp_f32_e32 v69, v0
	s_waitcnt vmcnt(31)
	v_fma_f32 v102, -v0, v69, 1.0
	v_fmac_f32_e32 v69, v102, v69
	v_div_scale_f32 v102, vcc, 1.0, v68, 1.0
	v_mul_f32_e32 v103, v102, v69
	v_fma_f32 v104, -v0, v103, v102
	v_fmac_f32_e32 v103, v104, v69
	v_fma_f32 v0, -v0, v103, v102
	v_div_fmas_f32 v0, v0, v69, v103
	v_div_fixup_f32 v68, v0, v68, 1.0
	v_pk_mul_f32 v[50:51], v[50:51], v[68:69] op_sel_hi:[1,0]
	v_lshlrev_b32_e32 v0, 1, v166
	v_pk_mul_f32 v[34:35], v[34:35], v[68:69] op_sel_hi:[1,0]
	v_pk_mul_f32 v[36:37], v[36:37], v[68:69] op_sel_hi:[1,0]
	v_pk_mul_f32 v[38:39], v[38:39], v[68:69] op_sel_hi:[1,0]
	v_pk_mul_f32 v[40:41], v[40:41], v[68:69] op_sel_hi:[1,0]
	v_pk_mul_f32 v[18:19], v[18:19], v[68:69] op_sel_hi:[1,0]
	v_pk_mul_f32 v[20:21], v[20:21], v[68:69] op_sel_hi:[1,0]
	v_pk_mul_f32 v[22:23], v[22:23], v[68:69] op_sel_hi:[1,0]
	v_pk_mul_f32 v[24:25], v[24:25], v[68:69] op_sel_hi:[1,0]
	v_pk_mul_f32 v[2:3], v[2:3], v[68:69] op_sel_hi:[1,0]
	v_pk_mul_f32 v[4:5], v[4:5], v[68:69] op_sel_hi:[1,0]
	v_pk_mul_f32 v[6:7], v[6:7], v[68:69] op_sel_hi:[1,0]
	v_pk_mul_f32 v[8:9], v[8:9], v[68:69] op_sel_hi:[1,0]
	s_waitcnt vmcnt(15)
	v_lshlrev_b32_e32 v102, 16, v98
	v_and_b32_e32 v103, 0xffff0000, v98
	v_pk_mul_f32 v[102:103], v[50:51], v[102:103]
	v_pk_mul_f32 v[50:51], v[52:53], v[68:69] op_sel_hi:[1,0]
	v_lshlrev_b32_e32 v52, 16, v99
	v_and_b32_e32 v53, 0xffff0000, v99
	v_pk_mul_f32 v[98:99], v[50:51], v[52:53]
	v_pk_mul_f32 v[50:51], v[54:55], v[68:69] op_sel_hi:[1,0]
	s_waitcnt vmcnt(14)
	v_lshlrev_b32_e32 v52, 16, v100
	v_and_b32_e32 v53, 0xffff0000, v100
	v_pk_mul_f32 v[54:55], v[50:51], v[52:53]
	v_pk_mul_f32 v[50:51], v[56:57], v[68:69] op_sel_hi:[1,0]
	v_lshlrev_b32_e32 v52, 16, v101
	v_and_b32_e32 v53, 0xffff0000, v101
	v_pk_mul_f32 v[56:57], v[50:51], v[52:53]
	v_lshl_add_u64 v[50:51], s[34:35], 0, v[96:97]
	v_lshl_add_u64 v[50:51], v[50:51], 0, s[0:1]
	v_cvt_pk_bf16_f32 v52, v102, v103
	v_cvt_pk_bf16_f32 v53, v98, v99
	v_cvt_pk_bf16_f32 v54, v54, v55
	v_cvt_pk_bf16_f32 v55, v56, v57
	v_lshl_add_u64 v[50:51], v[50:51], 0, v[0:1]
	v_permlane32_swap_b32_e32 v52, v54
	v_permlane32_swap_b32_e32 v53, v55
	global_store_dwordx4 v[50:51], v[52:55], off offset:2048
	s_waitcnt vmcnt(14)
	v_lshlrev_b32_e32 v56, 16, v95
	v_and_b32_e32 v57, 0xffff0000, v95
	v_pk_mul_f32 v[52:53], v[58:59], v[68:69] op_sel_hi:[1,0]
	v_lshlrev_b32_e32 v54, 16, v94
	v_and_b32_e32 v55, 0xffff0000, v94
	v_pk_mul_f32 v[52:53], v[52:53], v[54:55]
	v_pk_mul_f32 v[54:55], v[60:61], v[68:69] op_sel_hi:[1,0]
	s_waitcnt vmcnt(13)
	v_lshlrev_b32_e32 v58, 16, v92
	v_pk_mul_f32 v[54:55], v[54:55], v[56:57]
	v_pk_mul_f32 v[56:57], v[62:63], v[68:69] op_sel_hi:[1,0]
	v_and_b32_e32 v59, 0xffff0000, v92
	v_pk_mul_f32 v[56:57], v[56:57], v[58:59]
	v_pk_mul_f32 v[58:59], v[64:65], v[68:69] op_sel_hi:[1,0]
	v_lshlrev_b32_e32 v60, 16, v93
	v_and_b32_e32 v61, 0xffff0000, v93
	v_pk_mul_f32 v[58:59], v[58:59], v[60:61]
	v_cvt_pk_bf16_f32 v52, v52, v53
	v_cvt_pk_bf16_f32 v53, v54, v55
	v_cvt_pk_bf16_f32 v54, v56, v57
	v_cvt_pk_bf16_f32 v55, v58, v59
	s_nop 0
	v_permlane32_swap_b32_e32 v52, v54
	v_permlane32_swap_b32_e32 v53, v55
	global_store_dwordx4 v[50:51], v[52:55], off offset:2080
	s_waitcnt vmcnt(13)
	s_nop 0
	v_lshlrev_b32_e32 v52, 16, v90
	v_and_b32_e32 v53, 0xffff0000, v90
	v_pk_mul_f32 v[34:35], v[34:35], v[52:53]
	v_lshlrev_b32_e32 v52, 16, v91
	v_and_b32_e32 v53, 0xffff0000, v91
	v_pk_mul_f32 v[36:37], v[36:37], v[52:53]
	s_waitcnt vmcnt(12)
; DI float bf_lo(unsigned u) { return __uint_as_float(u << 16); }
; DI float bf_hi(unsigned u) { return __uint_as_float(u & 0xffff0000u); }
; DI void mla_unit(const Params& p, const int t, int l, int h, int qb, char* lds) {
;     ...
;   for (int dt = 0; dt < 4; ++dt)
; #pragma unroll
;     for (int a = 0; a < 2; ++a) {
;       float xy[2][4];
; #pragma unroll
;       for (int q2 = 0; q2 < 2; ++q2) {
;         const int g = 2 * a + q2;
;         const u32x2 z = zv[dt * 4 + g];
;         xy[q2][0] = o[dt][4 * g] * inv * bf_lo(z[0]); xy[q2][1] = o[dt][4 * g + 1] * inv * bf_hi(z[0]);
;         xy[q2][2] = o[dt][4 * g + 2] * inv * bf_lo(z[1]); xy[q2][3] = o[dt][4 * g + 3] * inv * bf_hi(z[1]);
;       }
;       st8_pair_bf16(p.MIX + (size_t)qrow * 2048 + 1024 + h * 128 + 32 * dt + 16 * a + 8 * hf, xy[0], xy[1]);
;     }
	v_lshlrev_b32_e32 v52, 16, v88
	v_and_b32_e32 v53, 0xffff0000, v88
	v_pk_mul_f32 v[38:39], v[38:39], v[52:53]
	v_lshlrev_b32_e32 v52, 16, v89
	v_and_b32_e32 v53, 0xffff0000, v89
	v_pk_mul_f32 v[40:41], v[40:41], v[52:53]
	v_cvt_pk_bf16_f32 v34, v34, v35
	v_cvt_pk_bf16_f32 v35, v36, v37
	v_cvt_pk_bf16_f32 v36, v38, v39
	v_cvt_pk_bf16_f32 v37, v40, v41
	s_nop 0
	v_permlane32_swap_b32_e32 v34, v36
	v_permlane32_swap_b32_e32 v35, v37
	global_store_dwordx4 v[50:51], v[34:37], off offset:2112
	s_waitcnt vmcnt(12)
	v_lshlrev_b32_e32 v38, 16, v87
	v_and_b32_e32 v39, 0xffff0000, v87
	v_pk_mul_f32 v[34:35], v[42:43], v[68:69] op_sel_hi:[1,0]
	v_lshlrev_b32_e32 v36, 16, v86
	v_and_b32_e32 v37, 0xffff0000, v86
	v_pk_mul_f32 v[34:35], v[34:35], v[36:37]
	v_pk_mul_f32 v[36:37], v[44:45], v[68:69] op_sel_hi:[1,0]
	s_waitcnt vmcnt(11)
	v_lshlrev_b32_e32 v40, 16, v84
	v_pk_mul_f32 v[36:37], v[36:37], v[38:39]
	v_pk_mul_f32 v[38:39], v[46:47], v[68:69] op_sel_hi:[1,0]
	v_and_b32_e32 v41, 0xffff0000, v84
	v_pk_mul_f32 v[38:39], v[38:39], v[40:41]
	v_pk_mul_f32 v[40:41], v[48:49], v[68:69] op_sel_hi:[1,0]
	v_lshlrev_b32_e32 v42, 16, v85
	v_and_b32_e32 v43, 0xffff0000, v85
	v_pk_mul_f32 v[40:41], v[40:41], v[42:43]
	v_cvt_pk_bf16_f32 v34, v34, v35
	v_cvt_pk_bf16_f32 v35, v36, v37
	v_cvt_pk_bf16_f32 v36, v38, v39
	v_cvt_pk_bf16_f32 v37, v40, v41
	s_nop 0
	v_permlane32_swap_b32_e32 v34, v36
	v_permlane32_swap_b32_e32 v35, v37
	global_store_dwordx4 v[50:51], v[34:37], off offset:2144
	s_waitcnt vmcnt(11)
	s_nop 0
	v_lshlrev_b32_e32 v34, 16, v82
	v_and_b32_e32 v35, 0xffff0000, v82
	v_pk_mul_f32 v[18:19], v[18:19], v[34:35]
	v_lshlrev_b32_e32 v34, 16, v83
	v_and_b32_e32 v35, 0xffff0000, v83
	v_pk_mul_f32 v[20:21], v[20:21], v[34:35]
	s_waitcnt vmcnt(10)
	v_lshlrev_b32_e32 v34, 16, v80
	v_and_b32_e32 v35, 0xffff0000, v80
	v_pk_mul_f32 v[22:23], v[22:23], v[34:35]
	v_lshlrev_b32_e32 v34, 16, v81
	v_and_b32_e32 v35, 0xffff0000, v81
	v_pk_mul_f32 v[24:25], v[24:25], v[34:35]
	v_cvt_pk_bf16_f32 v18, v18, v19
	v_cvt_pk_bf16_f32 v19, v20, v21
	v_cvt_pk_bf16_f32 v20, v22, v23
	v_cvt_pk_bf16_f32 v21, v24, v25
	s_nop 0
	v_permlane32_swap_b32_e32 v18, v20
	v_permlane32_swap_b32_e32 v19, v21
	global_store_dwordx4 v[50:51], v[18:21], off offset:2176
	s_waitcnt vmcnt(10)
	v_lshlrev_b32_e32 v22, 16, v79
	v_and_b32_e32 v23, 0xffff0000, v79
	v_pk_mul_f32 v[18:19], v[26:27], v[68:69] op_sel_hi:[1,0]
	v_lshlrev_b32_e32 v20, 16, v78
	v_and_b32_e32 v21, 0xffff0000, v78
	v_pk_mul_f32 v[18:19], v[18:19], v[20:21]
	v_pk_mul_f32 v[20:21], v[28:29], v[68:69] op_sel_hi:[1,0]
	s_waitcnt vmcnt(9)
	v_lshlrev_b32_e32 v24, 16, v76
	v_pk_mul_f32 v[20:21], v[20:21], v[22:23]
	v_pk_mul_f32 v[22:23], v[30:31], v[68:69] op_sel_hi:[1,0]
	v_and_b32_e32 v25, 0xffff0000, v76
	v_pk_mul_f32 v[22:23], v[22:23], v[24:25]
	v_pk_mul_f32 v[24:25], v[32:33], v[68:69] op_sel_hi:[1,0]
	v_lshlrev_b32_e32 v26, 16, v77
	v_and_b32_e32 v27, 0xffff0000, v77
	v_pk_mul_f32 v[24:25], v[24:25], v[26:27]
	v_cvt_pk_bf16_f32 v18, v18, v19
	v_cvt_pk_bf16_f32 v19, v20, v21
	v_cvt_pk_bf16_f32 v20, v22, v23
	v_cvt_pk_bf16_f32 v21, v24, v25
	s_nop 0
	v_permlane32_swap_b32_e32 v18, v20
	v_permlane32_swap_b32_e32 v19, v21
	global_store_dwordx4 v[50:51], v[18:21], off offset:2208
	s_waitcnt vmcnt(9)
	s_nop 0
	v_lshlrev_b32_e32 v18, 16, v74
	v_and_b32_e32 v19, 0xffff0000, v74
	v_pk_mul_f32 v[2:3], v[2:3], v[18:19]
	v_lshlrev_b32_e32 v18, 16, v75
	v_and_b32_e32 v19, 0xffff0000, v75
	v_pk_mul_f32 v[4:5], v[4:5], v[18:19]
	s_waitcnt vmcnt(8)
	v_lshlrev_b32_e32 v18, 16, v72
	v_and_b32_e32 v19, 0xffff0000, v72
	v_pk_mul_f32 v[6:7], v[6:7], v[18:19]
	v_lshlrev_b32_e32 v18, 16, v73
	v_and_b32_e32 v19, 0xffff0000, v73
	v_pk_mul_f32 v[8:9], v[8:9], v[18:19]
	v_cvt_pk_bf16_f32 v2, v2, v3
	v_cvt_pk_bf16_f32 v3, v4, v5
	v_cvt_pk_bf16_f32 v4, v6, v7
	v_cvt_pk_bf16_f32 v5, v8, v9
	s_nop 0
	v_permlane32_swap_b32_e32 v2, v4
	v_permlane32_swap_b32_e32 v3, v5
	global_store_dwordx4 v[50:51], v[2:5], off offset:2240
	s_waitcnt vmcnt(8)
	v_lshlrev_b32_e32 v6, 16, v71
	v_and_b32_e32 v7, 0xffff0000, v71
	v_pk_mul_f32 v[2:3], v[10:11], v[68:69] op_sel_hi:[1,0]
	v_lshlrev_b32_e32 v4, 16, v70
	v_and_b32_e32 v5, 0xffff0000, v70
	v_pk_mul_f32 v[2:3], v[2:3], v[4:5]
	v_pk_mul_f32 v[4:5], v[12:13], v[68:69] op_sel_hi:[1,0]
	s_waitcnt vmcnt(7)
	v_lshlrev_b32_e32 v8, 16, v66
	v_pk_mul_f32 v[4:5], v[4:5], v[6:7]
	v_pk_mul_f32 v[6:7], v[14:15], v[68:69] op_sel_hi:[1,0]
	v_and_b32_e32 v9, 0xffff0000, v66
	v_pk_mul_f32 v[6:7], v[6:7], v[8:9]
	v_pk_mul_f32 v[8:9], v[16:17], v[68:69] op_sel_hi:[1,0]
	v_lshlrev_b32_e32 v10, 16, v67
	v_and_b32_e32 v11, 0xffff0000, v67
	v_pk_mul_f32 v[8:9], v[8:9], v[10:11]
	v_cvt_pk_bf16_f32 v2, v2, v3
	v_cvt_pk_bf16_f32 v3, v4, v5
	v_cvt_pk_bf16_f32 v4, v6, v7
	v_cvt_pk_bf16_f32 v5, v8, v9
	s_nop 0
	v_permlane32_swap_b32_e32 v2, v4
	v_permlane32_swap_b32_e32 v3, v5
	global_store_dwordx4 v[50:51], v[2:5], off offset:2272

; #define AT_LOAD(TT) do { const u16* kn_ = Kp + (size_t)((TT) << 6) * ldk; const u16* vn_ = Vt + ((TT) << 6); \
;     _Pragma("unroll") for (int pi = 0; pi < 2; ++pi) vr[pi] = *(const u32x4*)(vn_ + (size_t)64 * pi * S + voff); \
;     _Pragma("unroll") for (int pi = 0; pi < NKC; ++pi) kr[pi] = *(const u32x4*)(kn_ + 64 * pi + koff); } while (0)
; template <int DQK, int KROW, bool BIAS, bool MAPS2>
; DI void attn_core(const int t, const u16* __restrict__ Q, int ldq, const u16* __restrict__ Kp, int ldk, const u16* __restrict__ Vt, int q0,
;                   char* lds, const float* lut, float b31, f32x16 (&o)[4], float& l_out) {
;     ...
;   bf16x8 qf[NKS];
; #pragma unroll
;   for (int ks = 0; ks < NKS; ++ks) qf[ks] = *(const bf16x8*)(Q + (size_t)qrow * ldq + map * DQK + 16 * ks + 8 * hf);
; #pragma unroll
;   for (int dt = 0; dt < 4; ++dt)
; #pragma unroll
;     for (int i = 0; i < 16; ++i) o[dt][i] = 0.f;
;   float m_run = 0.f, l_run = 0.f;
;   const int ntile = (q0 >> 6) + (MAPS2 ? 2 : 4);
;   u32x4 kr[NKC], vr[2];
;   const unsigned koff = (unsigned)(t >> 3) * (unsigned)ldk + (unsigned)(t & 7) * 8u;
;   const unsigned voff = (unsigned)(t >> 3) * (unsigned)S + (unsigned)(t & 7) * 8u;
;   char* const klds = lds + (t >> 3) * KS + (t & 7) * 16;
;   char* const vlds = lds + AT_VOFF + (t >> 3) * VS + ((t & 7) >> 1) * 32 + (t & 1) * 8;
;     ...
;   AT_LOAD(0);
;   __syncthreads();
;   AT_WRITE(0);
;   AT_LOAD(1);
;   __syncthreads();
.LBB0_266:
	s_andn2_b64 vcc, exec, s[0:1]
	s_cbranch_vccnz .LBB0_215
	s_lshl_b32 s0, s63, 8
	s_mul_i32 s4, s62, 0xc0
	s_sub_i32 s2, 0x1f00, s0
	s_lshl_b64 s[0:1], s[4:5], 1
	s_add_u32 s90, s24, s0
	s_addc_u32 s91, s25, s1
	s_add_u32 s0, s22, s0
	v_ashrrev_i32_e32 v0, 1, v233
	s_addc_u32 s1, s23, s1
	s_lshl_b32 s88, s62, 7
	s_mov_b32 s89, s5
	v_and_b32_e32 v0, 0xffffffe0, v0
	s_lshl_b64 s[62:63], s[88:89], 14
	v_and_b32_e32 v29, 7, v233
	v_add_u32_e32 v167, s2, v0
	s_add_u32 s62, s26, s62
	v_ashrrev_i32_e32 v28, 3, v233
	v_lshlrev_b32_e32 v0, 3, v29
	v_and_b32_e32 v26, 31, v233
	s_addc_u32 s63, s27, s63
	v_lshl_or_b32 v2, v28, 13, v0
	v_mov_b32_e32 v3, v1
	v_mul_lo_u32 v6, v28, s72
	v_bfe_u32 v27, v233, 5, 1
	v_lshl_add_u64 v[168:169], v[2:3], 1, s[62:63]
	v_or_b32_e32 v6, v6, v0
	v_mov_b32_e32 v7, v1
	v_or_b32_e32 v170, v167, v26
	v_mov_b64_e32 v[24:25], s[90:91]
	v_lshl_add_u64 v[172:173], v[6:7], 1, s[0:1]
	v_add_co_u32_e32 v22, vcc, s74, v168
	v_mad_i64_i32 v[24:25], s[0:1], v170, s99, v[24:25]
	v_lshlrev_b32_e32 v0, 4, v27
	v_addc_co_u32_e32 v23, vcc, 0, v169, vcc
	v_lshl_add_u64 v[24:25], v[24:25], 0, v[0:1]
	global_load_dwordx4 v[2:5], v[168:169], off
	global_load_dwordx4 v[6:9], v[172:173], off
	global_load_dwordx4 v[10:13], v[172:173], off offset:128
	global_load_dwordx4 v[14:17], v[172:173], off offset:256
	global_load_dwordx4 v[18:21], v[22:23], off
	global_load_dwordx4 v[98:101], v[24:25], off
	global_load_dwordx4 v[102:105], v[24:25], off offset:32
	global_load_dwordx4 v[106:109], v[24:25], off offset:64
	global_load_dwordx4 v[110:113], v[24:25], off offset:96
	global_load_dwordx4 v[114:117], v[24:25], off offset:128
	global_load_dwordx4 v[118:121], v[24:25], off offset:160
	global_load_dwordx4 v[122:125], v[24:25], off offset:192
	global_load_dwordx4 v[126:129], v[24:25], off offset:224
	global_load_dwordx4 v[130:133], v[24:25], off offset:256
	global_load_dwordx4 v[134:137], v[24:25], off offset:288
	global_load_dwordx4 v[138:141], v[24:25], off offset:320
	global_load_dwordx4 v[142:145], v[24:25], off offset:352
	v_add_co_u32_e32 v24, vcc, s59, v172
	s_mov_b64 s[0:1], 0x30000
	s_nop 0
	v_addc_co_u32_e32 v25, vcc, 0, v173, vcc
	s_barrier
	global_load_dwordx4 v[146:149], v[168:169], off offset:128
	global_load_dwordx4 v[150:153], v[22:23], off offset:128
	v_lshl_add_u64 v[22:23], v[172:173], 0, s[0:1]
	global_load_dwordx4 v[154:157], v[24:25], off
	global_load_dwordx4 v[158:161], v[22:23], off offset:128
	global_load_dwordx4 v[162:165], v[22:23], off offset:256
	v_mul_lo_u32 v23, v28, s75
	v_lshlrev_b32_e32 v24, 4, v29
	v_lshlrev_b32_e32 v25, 8, v28
	v_and_b32_e32 v28, 0x60, v24
	v_sub_u32_e32 v25, v23, v25
	v_lshlrev_b32_e32 v22, 3, v233
	v_add_u32_e32 v174, v23, v24
	v_add_u32_e32 v23, v25, v28
	v_and_or_b32 v175, v22, 8, v23
	v_add_u32_e32 v22, 0xc800, v175
	v_add_u32_e32 v23, 0xe800, v175
	v_mad_u32_u24 v178, v26, s75, v0
	v_lshlrev_b32_e32 v0, 8, v26
	v_lshlrev_b32_e32 v166, 3, v27
	v_lshlrev_b32_e32 v176, 2, v27
	v_sub_u32_e32 v179, v178, v0
	v_mov_b32_e32 v0, v1
	s_lshr_b32 s2, s2, 6
	s_mov_b32 s63, 0
	v_ashrrev_i32_e32 v171, 31, v170
	s_add_i32 s2, s2, 4
	v_or_b32_e32 v177, 31, v167
	v_mov_b32_e32 v180, 0
	s_movk_i32 s4, 0x80
	s_waitcnt vmcnt(20)
	ds_write_b128 v174, v[6:9]
	s_waitcnt vmcnt(19)
	ds_write_b128 v174, v[10:13] offset:128
	s_waitcnt vmcnt(18)
	ds_write_b128 v174, v[14:17] offset:256
	ds_write2_b64 v22, v[2:3], v[4:5] offset1:2
	s_waitcnt vmcnt(17)
	ds_write2_b64 v23, v[18:19], v[20:21] offset0:128 offset1:130
	v_mov_b32_e32 v14, v1
	v_mov_b32_e32 v15, v1
	v_mov_b32_e32 v2, v1
	v_mov_b32_e32 v3, v1
	v_mov_b32_e32 v4, v1
	v_mov_b32_e32 v5, v1
	v_mov_b32_e32 v6, v1
	v_mov_b32_e32 v7, v1
	v_mov_b32_e32 v8, v1
	v_mov_b32_e32 v9, v1
	v_mov_b32_e32 v10, v1
	v_mov_b32_e32 v11, v1
	v_mov_b32_e32 v12, v1
	v_mov_b32_e32 v13, v1
	v_mov_b64_e32 v[64:65], v[14:15]
	v_mov_b64_e32 v[48:49], v[14:15]
	v_mov_b64_e32 v[32:33], v[14:15]
	v_mov_b64_e32 v[62:63], v[12:13]
	v_mov_b64_e32 v[60:61], v[10:11]
	v_mov_b64_e32 v[58:59], v[8:9]
	v_mov_b64_e32 v[56:57], v[6:7]
	v_mov_b64_e32 v[54:55], v[4:5]
	v_mov_b64_e32 v[52:53], v[2:3]
	v_mov_b64_e32 v[50:51], v[0:1]
	v_mov_b64_e32 v[46:47], v[12:13]
	v_mov_b64_e32 v[44:45], v[10:11]
	v_mov_b64_e32 v[42:43], v[8:9]
	v_mov_b64_e32 v[40:41], v[6:7]
	v_mov_b64_e32 v[38:39], v[4:5]
	v_mov_b64_e32 v[36:37], v[2:3]
	v_mov_b64_e32 v[34:35], v[0:1]
	v_mov_b64_e32 v[30:31], v[12:13]
	v_mov_b64_e32 v[28:29], v[10:11]
	v_mov_b64_e32 v[26:27], v[8:9]
	v_mov_b64_e32 v[24:25], v[6:7]
	v_mov_b64_e32 v[22:23], v[4:5]
	v_mov_b64_e32 v[20:21], v[2:3]
	v_mov_b64_e32 v[18:19], v[0:1]
	v_mov_b64_e32 v[16:17], v[14:15]
	v_mov_b64_e32 v[14:15], v[12:13]
	v_mov_b64_e32 v[12:13], v[10:11]
	v_mov_b64_e32 v[10:11], v[8:9]
	v_mov_b64_e32 v[8:9], v[6:7]
	v_mov_b64_e32 v[6:7], v[4:5]
	v_mov_b64_e32 v[4:5], v[2:3]
	v_mov_b64_e32 v[2:3], v[0:1]
	v_mov_b32_e32 v0, 0
	s_waitcnt lgkmcnt(0)
	s_barrier
	v_readfirstlane_b32 s100, v233
	s_nop 3
	s_cmp_lt_u32 s100, 0x100
	s_cbranch_scc1 .Lsp_3
	s_setprio 1
.Lsp_3:
	s_add_i32 s53, s63, 1
	s_cmp_ge_u32 s53, s2
	s_cbranch_scc1 .LBB0_270

; #define MFMA32(a, b, c) __builtin_amdgcn_mfma_f32_32x32x16_bf16((a), (b), (c), 0, 0, 0)
; template <int DQK, int KROW, bool BIAS, bool MAPS2>
; DI void attn_core(const int t, const u16* __restrict__ Q, int ldq, const u16* __restrict__ Kp, int ldk, const u16* __restrict__ Vt, int q0,
;                   char* lds, const float* lut, float b31, f32x16 (&o)[4], float& l_out) {
;     ...
;     const bool live = (kt << 6) <= wq0 + 31;
;     if (live) {
;       const int k0 = kt << 6;
;       const bool far = BIAS && (wq0 - (k0 + 63) >= 128);
;       const float init = (far ? b31 : 0.f) - m_run;
; #pragma unroll
;       for (int k2 = 0; k2 < 2; ++k2)
; #pragma unroll
;         for (int i = 0; i < 16; ++i) s[k2][i] = init;
;       {
;         constexpr int QBS = (NKS > 4) ? 2 : 4, NBT = NKS / QBS;
;         bf16x8 kfb[2][QBS][2];
;         const char* kbase = lds + (kt & 1) * AT_KBUF + r * KS + hf * 16 + map * (DQK * 2);
; #pragma unroll
;         for (int jq = 0; jq < QBS; ++jq)
; #pragma unroll
;           for (int k2 = 0; k2 < 2; ++k2) kfb[0][jq][k2] = *(const bf16x8*)(kbase + 32 * k2 * KS + jq * 32);
; #pragma unroll
;         for (int b = 0; b < NBT; ++b) {
;           if (b + 1 < NBT) {
; #pragma unroll
;             for (int jq = 0; jq < QBS; ++jq)
; #pragma unroll
;               for (int k2 = 0; k2 < 2; ++k2) kfb[(b + 1) & 1][jq][k2] = *(const bf16x8*)(kbase + 32 * k2 * KS + ((b + 1) * QBS + jq) * 32);
;           }
;           __builtin_amdgcn_sched_barrier(0);
;           __builtin_amdgcn_s_setprio(1);
; #pragma unroll
;           for (int jq = 0; jq < QBS; ++jq)
; #pragma unroll
;             for (int k2 = 0; k2 < 2; ++k2) s[k2] = MFMA32(kfb[b & 1][jq][k2], qf[b * QBS + jq], s[k2]);
;           __builtin_amdgcn_s_setprio(0);
;           __builtin_amdgcn_sched_barrier(0);
;         }
.LBB0_270:
	s_add_i32 s0, s4, 0xffffff80
	v_cmp_le_i32_e32 vcc, s0, v177
	s_and_saveexec_b64 s[90:91], vcc
	s_cbranch_execz .LBB0_276
	s_and_b32 s62, s63, 1
	s_mul_i32 s0, s62, 0x6400
	v_add_u32_e32 v181, s0, v178
	ds_read_b128 v[182:185], v181
	ds_read_b128 v[186:189], v181 offset:32
	ds_read_b128 v[190:193], v181 offset:12800
	ds_read_b128 v[194:197], v181 offset:12832
	ds_read_b128 v[198:201], v181 offset:64
	ds_read_b128 v[202:205], v181 offset:96
	ds_read_b128 v[206:209], v181 offset:12864
	ds_read_b128 v[210:213], v181 offset:12896
	v_sub_f32_e32 v66, 0, v180
	v_mov_b32_e32 v67, v66
	v_mov_b32_e32 v68, v66
	v_mov_b32_e32 v69, v66
	v_mov_b32_e32 v70, v66
	v_mov_b32_e32 v71, v66
	v_mov_b32_e32 v72, v66
	v_mov_b32_e32 v73, v66
	v_mov_b32_e32 v74, v66
	v_mov_b32_e32 v75, v66
	v_mov_b32_e32 v76, v66
	v_mov_b32_e32 v77, v66
	v_mov_b32_e32 v78, v66
	v_mov_b32_e32 v79, v66
	v_mov_b32_e32 v80, v66
	v_mov_b32_e32 v81, v66
	s_waitcnt vmcnt(16) lgkmcnt(7)
	s_nop 0
	v_mfma_f32_32x32x16_bf16 v[82:97], v[182:185], v[98:101], v[66:81]
	s_waitcnt lgkmcnt(5)
	v_mfma_f32_32x32x16_bf16 v[66:81], v[190:193], v[98:101], v[66:81]
	s_waitcnt vmcnt(15)
	v_mfma_f32_32x32x16_bf16 v[82:97], v[186:189], v[102:105], v[82:97]
	s_waitcnt lgkmcnt(4)
	v_mfma_f32_32x32x16_bf16 v[66:81], v[194:197], v[102:105], v[66:81]
	ds_read_b128 v[182:185], v181 offset:128
	ds_read_b128 v[186:189], v181 offset:160
	ds_read_b128 v[190:193], v181 offset:12928
	ds_read_b128 v[194:197], v181 offset:12960
	s_waitcnt vmcnt(14) lgkmcnt(7)
	v_mfma_f32_32x32x16_bf16 v[82:97], v[198:201], v[106:109], v[82:97]
	s_waitcnt lgkmcnt(5)
	v_mfma_f32_32x32x16_bf16 v[66:81], v[206:209], v[106:109], v[66:81]
	s_waitcnt vmcnt(13)
	v_mfma_f32_32x32x16_bf16 v[82:97], v[202:205], v[110:113], v[82:97]
	s_waitcnt lgkmcnt(4)
	v_mfma_f32_32x32x16_bf16 v[66:81], v[210:213], v[110:113], v[66:81]
	ds_read_b128 v[198:201], v181 offset:192
	ds_read_b128 v[202:205], v181 offset:224
	ds_read_b128 v[206:209], v181 offset:12992
	ds_read_b128 v[210:213], v181 offset:13024
	s_waitcnt vmcnt(12) lgkmcnt(7)
	v_mfma_f32_32x32x16_bf16 v[82:97], v[182:185], v[114:117], v[82:97]
	s_waitcnt lgkmcnt(5)
	v_mfma_f32_32x32x16_bf16 v[66:81], v[190:193], v[114:117], v[66:81]
	s_waitcnt vmcnt(11)
	v_mfma_f32_32x32x16_bf16 v[82:97], v[186:189], v[118:121], v[82:97]
	s_waitcnt lgkmcnt(4)
	v_mfma_f32_32x32x16_bf16 v[66:81], v[194:197], v[118:121], v[66:81]
	ds_read_b128 v[182:185], v181 offset:256
	ds_read_b128 v[186:189], v181 offset:288
	ds_read_b128 v[190:193], v181 offset:13056
	ds_read_b128 v[194:197], v181 offset:13088
	s_waitcnt vmcnt(10) lgkmcnt(7)
	v_mfma_f32_32x32x16_bf16 v[82:97], v[198:201], v[122:125], v[82:97]
	s_waitcnt lgkmcnt(5)
	v_mfma_f32_32x32x16_bf16 v[66:81], v[206:209], v[122:125], v[66:81]
	s_waitcnt vmcnt(9)
	v_mfma_f32_32x32x16_bf16 v[82:97], v[202:205], v[126:129], v[82:97]
	s_waitcnt lgkmcnt(4)
	v_mfma_f32_32x32x16_bf16 v[66:81], v[210:213], v[126:129], v[66:81]
	ds_read_b128 v[198:201], v181 offset:320
	ds_read_b128 v[202:205], v181 offset:352
	ds_read_b128 v[206:209], v181 offset:13120
	ds_read_b128 v[210:213], v181 offset:13152
	s_waitcnt vmcnt(8) lgkmcnt(7)
	v_mfma_f32_32x32x16_bf16 v[82:97], v[182:185], v[130:133], v[82:97]
	s_waitcnt lgkmcnt(5)
	v_mfma_f32_32x32x16_bf16 v[66:81], v[190:193], v[130:133], v[66:81]
	s_waitcnt vmcnt(7)
	v_mfma_f32_32x32x16_bf16 v[82:97], v[186:189], v[134:137], v[82:97]
	s_waitcnt lgkmcnt(4)
	v_mfma_f32_32x32x16_bf16 v[66:81], v[194:197], v[134:137], v[66:81]
	s_waitcnt vmcnt(6) lgkmcnt(3)
	v_mfma_f32_32x32x16_bf16 v[82:97], v[198:201], v[138:141], v[82:97]
	s_waitcnt lgkmcnt(1)
	v_mfma_f32_32x32x16_bf16 v[66:81], v[206:209], v[138:141], v[66:81]
	s_waitcnt vmcnt(5)
	v_mfma_f32_32x32x16_bf16 v[82:97], v[202:205], v[142:145], v[82:97]
	s_waitcnt lgkmcnt(0)
	v_mfma_f32_32x32x16_bf16 v[66:81], v[210:213], v[142:145], v[66:81]
	s_add_i32 s0, s4, 0xffffffbf
	v_cmp_gt_i32_e32 vcc, s0, v167
	s_and_saveexec_b64 s[0:1], vcc
	s_cbranch_execz .LBB0_273
; template <int DQK, int KROW, bool BIAS, bool MAPS2>
; DI void attn_core(const int t, const u16* __restrict__ Q, int ldq, const u16* __restrict__ Kp, int ldk, const u16* __restrict__ Vt, int q0,
;                   char* lds, const float* lut, float b31, f32x16 (&o)[4], float& l_out) {
;     ...
;       if (k0 + 63 > wq0) {
; #pragma unroll
;         for (int k2 = 0; k2 < 2; ++k2)
; #pragma unroll
;           for (int i = 0; i < 16; ++i) {
;             const int key = k0 + 32 * k2 + (i & 3) + 8 * (i >> 2) + 4 * hf;
;             if (key > qrow) s[k2][i] = -INFINITY;
;           }
;       }
	v_add_u32_e32 v181, s4, v176
	v_add_u32_e32 v182, 0xffffff80, v181
	v_cmp_gt_i32_e32 vcc, v182, v170
	s_nop 1
	v_cndmask_b32_e32 v183, v82, v230, vcc
	v_cmp_lt_i32_e32 vcc, v182, v170
	v_add_u32_e32 v182, 0xffffff82, v181
	s_nop 0
	v_cndmask_b32_e32 v82, v183, v82, vcc
	v_cndmask_b32_e32 v83, v230, v83, vcc
	v_cmp_le_i32_e32 vcc, v182, v170
	v_add_u32_e32 v182, 0xffffff83, v181
	s_nop 0
	v_cndmask_b32_e32 v84, v230, v84, vcc
	v_cmp_le_i32_e32 vcc, v182, v170
	v_add_u32_e32 v182, 0xffffff88, v181
	s_nop 0
	v_cndmask_b32_e32 v85, v230, v85, vcc
	v_cmp_le_i32_e32 vcc, v182, v170
	v_add_u32_e32 v182, 0xffffff89, v181
	s_nop 0
	v_cndmask_b32_e32 v86, v230, v86, vcc
	v_cmp_le_i32_e32 vcc, v182, v170
	v_add_u32_e32 v182, 0xffffff8a, v181
	s_nop 0
	v_cndmask_b32_e32 v87, v230, v87, vcc
	v_cmp_le_i32_e32 vcc, v182, v170
	v_add_u32_e32 v182, 0xffffff8b, v181
	s_nop 0
	v_cndmask_b32_e32 v88, v230, v88, vcc
	v_cmp_le_i32_e32 vcc, v182, v170
	v_add_u32_e32 v182, 0xffffff90, v181
	s_nop 0
	v_cndmask_b32_e32 v89, v230, v89, vcc
	v_cmp_le_i32_e32 vcc, v182, v170
	v_add_u32_e32 v182, 0xffffff91, v181
	s_nop 0
	v_cndmask_b32_e32 v90, v230, v90, vcc
	v_cmp_le_i32_e32 vcc, v182, v170
	v_add_u32_e32 v182, 0xffffff92, v181
	s_nop 0
	v_cndmask_b32_e32 v91, v230, v91, vcc
	v_cmp_le_i32_e32 vcc, v182, v170
	v_add_u32_e32 v182, 0xffffff93, v181
	s_nop 0
	v_cndmask_b32_e32 v92, v230, v92, vcc
	v_cmp_le_i32_e32 vcc, v182, v170
	v_add_u32_e32 v182, 0xffffff98, v181
	s_nop 0
	v_cndmask_b32_e32 v93, v230, v93, vcc
	v_cmp_le_i32_e32 vcc, v182, v170
	v_add_u32_e32 v182, 0xffffff99, v181
	s_nop 0
	v_cndmask_b32_e32 v94, v230, v94, vcc
	v_cmp_le_i32_e32 vcc, v182, v170
	v_add_u32_e32 v182, 0xffffff9a, v181
	s_nop 0
	v_cndmask_b32_e32 v95, v230, v95, vcc
	v_cmp_le_i32_e32 vcc, v182, v170
	v_add_u32_e32 v182, 0xffffff9b, v181
	s_nop 0
	v_cndmask_b32_e32 v96, v230, v96, vcc
	v_cmp_le_i32_e32 vcc, v182, v170
	v_add_u32_e32 v182, 0xffffffa0, v181
	s_nop 0
	v_cndmask_b32_e32 v97, v230, v97, vcc
	v_cmp_le_i32_e32 vcc, v182, v170
	v_add_u32_e32 v182, 0xffffffa1, v181
	s_nop 0
	v_cndmask_b32_e32 v66, v230, v66, vcc
	v_cmp_le_i32_e32 vcc, v182, v170
	v_add_u32_e32 v182, 0xffffffa2, v181
	s_nop 0
	v_cndmask_b32_e32 v67, v230, v67, vcc
	v_cmp_le_i32_e32 vcc, v182, v170
	v_add_u32_e32 v182, 0xffffffa3, v181
	s_nop 0
	v_cndmask_b32_e32 v68, v230, v68, vcc
	v_cmp_le_i32_e32 vcc, v182, v170
	v_add_u32_e32 v182, 0xffffffa8, v181
	s_nop 0
	v_cndmask_b32_e32 v69, v230, v69, vcc
	v_cmp_le_i32_e32 vcc, v182, v170
	v_add_u32_e32 v182, 0xffffffa9, v181
	s_nop 0
	v_cndmask_b32_e32 v70, v230, v70, vcc
	v_cmp_le_i32_e32 vcc, v182, v170
	v_add_u32_e32 v182, 0xffffffaa, v181
	s_nop 0
	v_cndmask_b32_e32 v71, v230, v71, vcc
	v_cmp_le_i32_e32 vcc, v182, v170
	v_add_u32_e32 v182, 0xffffffab, v181
	s_nop 0
	v_cndmask_b32_e32 v72, v230, v72, vcc
	v_cmp_le_i32_e32 vcc, v182, v170
	v_add_u32_e32 v182, 0xffffffb0, v181
	s_nop 0
	v_cndmask_b32_e32 v73, v230, v73, vcc
	v_cmp_le_i32_e32 vcc, v182, v170
	v_add_u32_e32 v182, 0xffffffb1, v181
	s_nop 0
	v_cndmask_b32_e32 v74, v230, v74, vcc
	v_cmp_le_i32_e32 vcc, v182, v170
	v_add_u32_e32 v182, 0xffffffb2, v181
	s_nop 0
	v_cndmask_b32_e32 v75, v230, v75, vcc
	v_cmp_le_i32_e32 vcc, v182, v170
	v_add_u32_e32 v182, 0xffffffb3, v181
	s_nop 0
	v_cndmask_b32_e32 v76, v230, v76, vcc
	v_cmp_le_i32_e32 vcc, v182, v170
	v_add_u32_e32 v182, 0xffffffb8, v181
	s_nop 0
	v_cndmask_b32_e32 v77, v230, v77, vcc
	v_cmp_le_i32_e32 vcc, v182, v170
	v_add_u32_e32 v182, 0xffffffb9, v181
	s_nop 0
	v_cndmask_b32_e32 v78, v230, v78, vcc
	v_cmp_le_i32_e32 vcc, v182, v170
	v_add_u32_e32 v182, 0xffffffba, v181
	v_add_u32_e32 v181, 0xffffffbb, v181
	v_cndmask_b32_e32 v79, v230, v79, vcc
	v_cmp_le_i32_e32 vcc, v182, v170
	s_nop 1
	v_cndmask_b32_e32 v80, v230, v80, vcc
	v_cmp_le_i32_e32 vcc, v181, v170
	s_nop 1
	v_cndmask_b32_e32 v81, v230, v81, vcc

; #define MFMA32(a, b, c) __builtin_amdgcn_mfma_f32_32x32x16_bf16((a), (b), (c), 0, 0, 0)
; template <int DQK, int KROW, bool BIAS, bool MAPS2>
; DI void attn_core(const int t, const u16* __restrict__ Q, int ldq, const u16* __restrict__ Kp, int ldk, const u16* __restrict__ Vt, int q0,
;                   char* lds, const float* lut, float b31, f32x16 (&o)[4], float& l_out) {
;     ...
;       float ps = 0.f;
; #pragma unroll
;       for (int k2 = 0; k2 < 2; ++k2)
; #pragma unroll
;         for (int i = 0; i < 16; ++i) { const float pv = __builtin_amdgcn_exp2f(s[k2][i]); s[k2][i] = pv; ps += pv; }
;       l_run += ps;
;       bf16x8 vfb[2][4];
;       const char* vbase = lds + AT_VOFF + (kt & 1) * AT_VBUF + r * VS + hf * 16;
; #pragma unroll
;       for (int dt = 0; dt < 4; ++dt) vfb[0][dt] = *(const bf16x8*)(vbase + 32 * dt * VS);
; #pragma unroll
;       for (int bb = 0; bb < 4; ++bb) {
;         const int k2 = bb >> 1, s2 = bb & 1;
;         if (bb + 1 < 4) {
; #pragma unroll
;           for (int dt = 0; dt < 4; ++dt) vfb[(bb + 1) & 1][dt] = *(const bf16x8*)(vbase + 32 * dt * VS + (bb + 1) * 32);
;         }
;         u32x4 pp;
;         pp[0] = pk_bf16(s[k2][8 * s2 + 0], s[k2][8 * s2 + 1]);
;         pp[1] = pk_bf16(s[k2][8 * s2 + 2], s[k2][8 * s2 + 3]);
;         pp[2] = pk_bf16(s[k2][8 * s2 + 4], s[k2][8 * s2 + 5]);
;         pp[3] = pk_bf16(s[k2][8 * s2 + 6], s[k2][8 * s2 + 7]);
;         const bf16x8 pf = __builtin_bit_cast(bf16x8, pp);
;         __builtin_amdgcn_sched_barrier(0);
;         __builtin_amdgcn_s_setprio(1);
; #pragma unroll
;         for (int dt = 0; dt < 4; ++dt) o[dt] = MFMA32(vfb[bb & 1][dt], pf, o[dt]);
;         __builtin_amdgcn_s_setprio(0);
;         __builtin_amdgcn_sched_barrier(0);
;       }
.LBB0_275:
	v_exp_f32_e32 v181, v82
	v_exp_f32_e32 v182, v83
	v_exp_f32_e32 v183, v84
	v_exp_f32_e32 v184, v85
	v_add_f32_e32 v82, 0, v181
	v_exp_f32_e32 v185, v86
	v_add_f32_e32 v82, v182, v82
	v_exp_f32_e32 v186, v87
	v_add_f32_e32 v82, v183, v82
	v_exp_f32_e32 v187, v88
	v_add_f32_e32 v82, v184, v82
	v_exp_f32_e32 v188, v89
	v_add_f32_e32 v82, v185, v82
	v_exp_f32_e32 v189, v90
	v_add_f32_e32 v82, v186, v82
	v_exp_f32_e32 v190, v91
	v_add_f32_e32 v82, v187, v82
	v_exp_f32_e32 v191, v92
	v_add_f32_e32 v82, v188, v82
	v_exp_f32_e32 v192, v93
	v_add_f32_e32 v82, v189, v82
	v_exp_f32_e32 v193, v94
	v_add_f32_e32 v82, v190, v82
	v_exp_f32_e32 v194, v95
	v_add_f32_e32 v82, v191, v82
	v_exp_f32_e32 v195, v96
	v_add_f32_e32 v82, v192, v82
	v_exp_f32_e32 v196, v97
	v_add_f32_e32 v82, v193, v82
	v_exp_f32_e32 v197, v66
	v_add_f32_e32 v82, v194, v82
	v_exp_f32_e32 v198, v67
	v_add_f32_e32 v82, v195, v82
	v_exp_f32_e32 v199, v68
	v_add_f32_e32 v82, v196, v82
	v_exp_f32_e32 v200, v69
	v_add_f32_e32 v66, v197, v82
	v_exp_f32_e32 v201, v70
	v_add_f32_e32 v66, v198, v66
	v_exp_f32_e32 v202, v71
	v_add_f32_e32 v66, v199, v66
	v_exp_f32_e32 v203, v72
	v_add_f32_e32 v66, v200, v66
	v_exp_f32_e32 v204, v73
	v_add_f32_e32 v66, v201, v66
	v_exp_f32_e32 v205, v74
	v_add_f32_e32 v66, v202, v66
	v_exp_f32_e32 v206, v75
	v_add_f32_e32 v66, v203, v66
	v_exp_f32_e32 v207, v76
	v_add_f32_e32 v66, v204, v66
	v_exp_f32_e32 v208, v77
	v_add_f32_e32 v66, v205, v66
	v_exp_f32_e32 v209, v78
	v_add_f32_e32 v66, v206, v66
	v_exp_f32_e32 v210, v79
	v_add_f32_e32 v66, v207, v66
	v_exp_f32_e32 v211, v80
	v_add_f32_e32 v66, v208, v66
	v_exp_f32_e32 v212, v81
	v_add_f32_e32 v66, v209, v66
	v_add_f32_e32 v66, v210, v66
	s_mulk_i32 s62, 0x4800
	v_add_f32_e32 v66, v211, v66
	v_add_u32_e32 v214, s62, v179
	v_add_f32_e32 v213, v212, v66
	ds_read_b128 v[66:69], v214 offset:51200
	ds_read_b128 v[70:73], v214 offset:51232
	ds_read_b128 v[74:77], v214 offset:55808
	ds_read_b128 v[78:81], v214 offset:55840
	ds_read_b128 v[82:85], v214 offset:60416
	ds_read_b128 v[86:89], v214 offset:60448
	ds_read_b128 v[90:93], v214 offset:65024
	ds_read_b128 v[94:97], v214 offset:65056
	v_cvt_pk_bf16_f32 v182, v181, v182
	v_cvt_pk_bf16_f32 v183, v183, v184
	v_cvt_pk_bf16_f32 v184, v185, v186
	v_cvt_pk_bf16_f32 v185, v187, v188
	s_waitcnt lgkmcnt(7)
	v_mfma_f32_32x32x16_bf16 v[50:65], v[66:69], v[182:185], v[50:65]
	s_waitcnt lgkmcnt(5)
	v_mfma_f32_32x32x16_bf16 v[34:49], v[74:77], v[182:185], v[34:49]
	s_waitcnt lgkmcnt(3)
	v_mfma_f32_32x32x16_bf16 v[18:33], v[82:85], v[182:185], v[18:33]
	s_waitcnt lgkmcnt(1)
	v_mfma_f32_32x32x16_bf16 v[2:17], v[90:93], v[182:185], v[2:17]
	ds_read_b128 v[66:69], v214 offset:51264
	ds_read_b128 v[74:77], v214 offset:55872
	ds_read_b128 v[82:85], v214 offset:60480
	ds_read_b128 v[90:93], v214 offset:65088
	v_cvt_pk_bf16_f32 v182, v189, v190
	v_cvt_pk_bf16_f32 v183, v191, v192
	v_cvt_pk_bf16_f32 v184, v193, v194
	v_cvt_pk_bf16_f32 v185, v195, v196
	s_nop 0
	v_mfma_f32_32x32x16_bf16 v[50:65], v[70:73], v[182:185], v[50:65]
	v_mfma_f32_32x32x16_bf16 v[34:49], v[78:81], v[182:185], v[34:49]
	v_mfma_f32_32x32x16_bf16 v[18:33], v[86:89], v[182:185], v[18:33]
	s_waitcnt lgkmcnt(4)
	v_mfma_f32_32x32x16_bf16 v[2:17], v[94:97], v[182:185], v[2:17]
	ds_read_b128 v[70:73], v214 offset:51296
	ds_read_b128 v[78:81], v214 offset:55904
	ds_read_b128 v[86:89], v214 offset:60512
	ds_read_b128 v[94:97], v214 offset:65120
	v_cvt_pk_bf16_f32 v182, v197, v198
	v_cvt_pk_bf16_f32 v183, v199, v200
	v_cvt_pk_bf16_f32 v184, v201, v202
	v_cvt_pk_bf16_f32 v185, v203, v204
	s_waitcnt lgkmcnt(7)
	v_mfma_f32_32x32x16_bf16 v[50:65], v[66:69], v[182:185], v[50:65]
	s_waitcnt lgkmcnt(6)
	v_mfma_f32_32x32x16_bf16 v[34:49], v[74:77], v[182:185], v[34:49]
	s_waitcnt lgkmcnt(5)
	v_mfma_f32_32x32x16_bf16 v[18:33], v[82:85], v[182:185], v[18:33]
	s_waitcnt lgkmcnt(4)
	v_mfma_f32_32x32x16_bf16 v[2:17], v[90:93], v[182:185], v[2:17]
	v_cvt_pk_bf16_f32 v66, v205, v206
	v_cvt_pk_bf16_f32 v67, v207, v208
	v_cvt_pk_bf16_f32 v68, v209, v210
	v_cvt_pk_bf16_f32 v69, v211, v212
	s_waitcnt lgkmcnt(3)
	v_mfma_f32_32x32x16_bf16 v[50:65], v[70:73], v[66:69], v[50:65]
	s_waitcnt lgkmcnt(2)
	v_mfma_f32_32x32x16_bf16 v[34:49], v[78:81], v[66:69], v[34:49]
	s_waitcnt lgkmcnt(1)
	v_mfma_f32_32x32x16_bf16 v[18:33], v[86:89], v[66:69], v[18:33]
	s_waitcnt lgkmcnt(0)
	v_mfma_f32_32x32x16_bf16 v[2:17], v[94:97], v[66:69], v[2:17]
	v_add_f32_e32 v0, v0, v213
